# E-MFMA with plain v_mul_f32 instead of v_pk_mul_f32 in the embedded epilogue blocks
# baseline (speedup 1.0000x reference)
.LBB0_268:
	v_add_u32_e32 v160, s43, v1
	ds_read_b128 v[156:159], v160
	ds_read_b128 v[162:165], v160 offset:1024
	ds_read_b128 v[166:169], v160 offset:2048
	ds_read_b128 v[170:173], v160 offset:3072
	v_add_u32_e32 v160, s44, v1
	ds_read_b128 v[174:177], v160
	ds_read_b128 v[178:181], v160 offset:1024
	ds_read_b128 v[182:185], v160 offset:2048
	ds_read_b128 v[192:195], v160 offset:3072
	s_add_u32 s52, s30, 0x10000
	s_addc_u32 s53, s31, 0
	s_cmp_eq_u32 s67, 12
	s_cselect_b32 s64, s51, s52
	s_cselect_b32 s65, s50, s53
	s_cselect_b32 s62, s55, s61
	s_cselect_b32 s63, s54, s66
	s_add_u32 s56, s64, 0x8000
	s_addc_u32 s57, s65, 0
	s_add_i32 m0, s36, 0xc000
	ds_read_b128 v[200:203], v155
	ds_read_b128 v[204:207], v155 offset:1024
	ds_read_b128 v[208:211], v155 offset:2048
	ds_read_b128 v[212:215], v155 offset:3072
	ds_read_b128 v[216:219], v155 offset:4096
	ds_read_b128 v[220:223], v155 offset:5120
	ds_read_b128 v[224:227], v155 offset:6144
	ds_read_b128 v[228:231], v155 offset:7168
	global_load_lds_dwordx4 v146, s[30:31] sc1
	s_add_i32 m0, s36, 0xe000
	s_nop 0
	global_load_lds_dwordx4 v148, s[30:31] sc1
	s_waitcnt vmcnt(8)
	s_waitcnt lgkmcnt(0)
	s_setprio 1
	s_barrier
	v_mfma_f32_16x16x32_bf16 v[118:121], v[156:159], v[200:203], v[118:121]
	v_mfma_f32_16x16x32_bf16 v[110:113], v[166:169], v[200:203], v[110:113]
	v_mfma_f32_16x16x32_bf16 v[102:105], v[156:159], v[208:211], v[102:105]
	v_mfma_f32_16x16x32_bf16 v[94:97], v[166:169], v[208:211], v[94:97]
	v_mfma_f32_16x16x32_bf16 v[86:89], v[156:159], v[216:219], v[86:89]
	v_mfma_f32_16x16x32_bf16 v[78:81], v[166:169], v[216:219], v[78:81]
	v_mfma_f32_16x16x32_bf16 v[62:65], v[156:159], v[224:227], v[62:65]
	v_mfma_f32_16x16x32_bf16 v[54:57], v[166:169], v[224:227], v[54:57]
	v_mfma_f32_16x16x32_bf16 v[118:121], v[162:165], v[204:207], v[118:121]
	v_mfma_f32_16x16x32_bf16 v[110:113], v[170:173], v[204:207], v[110:113]
	v_mfma_f32_16x16x32_bf16 v[102:105], v[162:165], v[212:215], v[102:105]
	v_mfma_f32_16x16x32_bf16 v[94:97], v[170:173], v[212:215], v[94:97]
	v_mfma_f32_16x16x32_bf16 v[86:89], v[162:165], v[220:223], v[86:89]
	v_mfma_f32_16x16x32_bf16 v[78:81], v[170:173], v[220:223], v[78:81]
	v_mfma_f32_16x16x32_bf16 v[62:65], v[162:165], v[228:231], v[62:65]
	v_mfma_f32_16x16x32_bf16 v[54:57], v[170:173], v[228:231], v[54:57]
	v_mfma_f32_16x16x32_bf16 v[126:129], v[174:177], v[200:203], v[126:129]
	v_mfma_f32_16x16x32_bf16 v[122:125], v[182:185], v[200:203], v[122:125]
	v_mfma_f32_16x16x32_bf16 v[114:117], v[174:177], v[208:211], v[114:117]
	v_mfma_f32_16x16x32_bf16 v[106:109], v[182:185], v[208:211], v[106:109]
	v_mfma_f32_16x16x32_bf16 v[98:101], v[174:177], v[216:219], v[98:101]
	v_mfma_f32_16x16x32_bf16 v[90:93], v[182:185], v[216:219], v[90:93]
	v_mfma_f32_16x16x32_bf16 v[82:85], v[174:177], v[224:227], v[82:85]
	v_mfma_f32_16x16x32_bf16 v[70:73], v[182:185], v[224:227], v[70:73]
	v_mfma_f32_16x16x32_bf16 v[126:129], v[178:181], v[204:207], v[126:129]
	v_mfma_f32_16x16x32_bf16 v[122:125], v[192:195], v[204:207], v[122:125]
	v_mfma_f32_16x16x32_bf16 v[114:117], v[178:181], v[212:215], v[114:117]
	v_mfma_f32_16x16x32_bf16 v[106:109], v[192:195], v[212:215], v[106:109]
	v_mfma_f32_16x16x32_bf16 v[98:101], v[178:181], v[220:223], v[98:101]
	v_mfma_f32_16x16x32_bf16 v[90:93], v[192:195], v[220:223], v[90:93]
	s_setprio 2
	s_barrier
	v_mfma_f32_16x16x32_bf16 v[82:85], v[178:181], v[228:231], v[82:85]
	v_mfma_f32_16x16x32_bf16 v[70:73], v[192:195], v[228:231], v[70:73]
	s_setprio 0
	s_add_i32 s30, s43, s5
	s_mov_b32 m0, s30
	ds_read_b128 v[200:203], v155 offset:16384
	ds_read_b128 v[204:207], v155 offset:17408
	ds_read_b128 v[208:211], v155 offset:18432
	ds_read_b128 v[212:215], v155 offset:19456
	ds_read_b128 v[216:219], v155 offset:20480
	ds_read_b128 v[220:223], v155 offset:21504
	ds_read_b128 v[224:227], v155 offset:22528
	ds_read_b128 v[228:231], v155 offset:23552
	global_load_lds_dwordx4 v134, s[62:63] sc1
	s_add_i32 m0, s30, 0x2000
	s_add_u32 s30, s62, 0x4000
	s_addc_u32 s31, s63, 0
	s_add_i32 s69, s44, s5
	global_load_lds_dwordx4 v136, s[62:63] sc1
	s_mov_b32 m0, s69
	s_nop 0
	global_load_lds_dwordx4 v134, s[30:31] sc1
	s_add_i32 m0, s69, 0x2000
	s_nop 0
	global_load_lds_dwordx4 v136, s[30:31] sc1
	s_mov_b32 m0, s36
	s_nop 0
	global_load_lds_dwordx4 v132, s[64:65] sc1
	s_mov_b32 m0, s37
	s_nop 0
	global_load_lds_dwordx4 v130, s[64:65] sc1
	s_waitcnt vmcnt(8)
	s_waitcnt lgkmcnt(0)
	s_setprio 1
	s_barrier
	v_mfma_f32_16x16x32_bf16 v[58:61], v[156:159], v[200:203], v[58:61]
	v_mfma_f32_16x16x32_bf16 v[46:49], v[166:169], v[200:203], v[46:49]
	v_mfma_f32_16x16x32_bf16 v[38:41], v[156:159], v[208:211], v[38:41]
	v_mfma_f32_16x16x32_bf16 v[30:33], v[166:169], v[208:211], v[30:33]
	v_mfma_f32_16x16x32_bf16 v[22:25], v[156:159], v[216:219], v[22:25]
	v_mfma_f32_16x16x32_bf16 v[14:17], v[166:169], v[216:219], v[14:17]
	v_mfma_f32_16x16x32_bf16 v[6:9], v[156:159], v[224:227], v[6:9]
	v_mfma_f32_16x16x32_bf16 v[2:5], v[166:169], v[224:227], v[2:5]
	v_mfma_f32_16x16x32_bf16 v[58:61], v[162:165], v[204:207], v[58:61]
	v_mfma_f32_16x16x32_bf16 v[46:49], v[170:173], v[204:207], v[46:49]
	v_mfma_f32_16x16x32_bf16 v[38:41], v[162:165], v[212:215], v[38:41]
	v_mfma_f32_16x16x32_bf16 v[30:33], v[170:173], v[212:215], v[30:33]
	v_mfma_f32_16x16x32_bf16 v[22:25], v[162:165], v[220:223], v[22:25]
	v_mfma_f32_16x16x32_bf16 v[14:17], v[170:173], v[220:223], v[14:17]
	v_mfma_f32_16x16x32_bf16 v[6:9], v[162:165], v[228:231], v[6:9]
	v_mfma_f32_16x16x32_bf16 v[2:5], v[170:173], v[228:231], v[2:5]
	v_mfma_f32_16x16x32_bf16 v[74:77], v[174:177], v[200:203], v[74:77]
	v_mfma_f32_16x16x32_bf16 v[66:69], v[182:185], v[200:203], v[66:69]
	v_mfma_f32_16x16x32_bf16 v[50:53], v[174:177], v[208:211], v[50:53]
	v_mfma_f32_16x16x32_bf16 v[42:45], v[182:185], v[208:211], v[42:45]
	v_mfma_f32_16x16x32_bf16 v[34:37], v[174:177], v[216:219], v[34:37]
	v_mfma_f32_16x16x32_bf16 v[26:29], v[182:185], v[216:219], v[26:29]
	v_mfma_f32_16x16x32_bf16 v[18:21], v[174:177], v[224:227], v[18:21]
	v_mfma_f32_16x16x32_bf16 v[10:13], v[182:185], v[224:227], v[10:13]
	v_mfma_f32_16x16x32_bf16 v[74:77], v[178:181], v[204:207], v[74:77]
	v_mfma_f32_16x16x32_bf16 v[66:69], v[192:195], v[204:207], v[66:69]
	v_mfma_f32_16x16x32_bf16 v[50:53], v[178:181], v[212:215], v[50:53]
	v_mfma_f32_16x16x32_bf16 v[42:45], v[192:195], v[212:215], v[42:45]
	v_mfma_f32_16x16x32_bf16 v[34:37], v[178:181], v[220:223], v[34:37]
	v_mfma_f32_16x16x32_bf16 v[26:29], v[192:195], v[220:223], v[26:29]
	s_setprio 2
	s_barrier
	v_mfma_f32_16x16x32_bf16 v[18:21], v[178:181], v[228:231], v[18:21]
	v_mfma_f32_16x16x32_bf16 v[10:13], v[192:195], v[228:231], v[10:13]
	s_setprio 0
	v_add_u32_e32 v160, s45, v1
	ds_read_b128 v[156:159], v160
	ds_read_b128 v[162:165], v160 offset:1024
	ds_read_b128 v[166:169], v160 offset:2048
	ds_read_b128 v[170:173], v160 offset:3072
	v_add_u32_e32 v160, s46, v1
	ds_read_b128 v[174:177], v160
	ds_read_b128 v[178:181], v160 offset:1024
	ds_read_b128 v[182:185], v160 offset:2048
	ds_read_b128 v[192:195], v160 offset:3072
	s_add_u32 s30, s64, 0x4000
	s_addc_u32 s31, s65, 0
	s_mov_b32 m0, s38
	ds_read_b128 v[200:203], v155 offset:32768
	ds_read_b128 v[204:207], v155 offset:33792
	ds_read_b128 v[208:211], v155 offset:34816
	ds_read_b128 v[212:215], v155 offset:35840
	ds_read_b128 v[216:219], v155 offset:36864
	ds_read_b128 v[220:223], v155 offset:37888
	ds_read_b128 v[224:227], v155 offset:38912
	ds_read_b128 v[228:231], v155 offset:39936
	global_load_lds_dwordx4 v132, s[30:31] sc1
	s_mov_b32 m0, s39
	s_nop 0
	global_load_lds_dwordx4 v130, s[30:31] sc1
	s_waitcnt vmcnt(8)
	s_waitcnt lgkmcnt(0)
	s_setprio 1
	s_barrier
	v_mfma_f32_16x16x32_bf16 v[118:121], v[156:159], v[200:203], v[118:121]
	v_mfma_f32_16x16x32_bf16 v[110:113], v[166:169], v[200:203], v[110:113]
	v_mfma_f32_16x16x32_bf16 v[102:105], v[156:159], v[208:211], v[102:105]
	v_mfma_f32_16x16x32_bf16 v[94:97], v[166:169], v[208:211], v[94:97]
	v_mfma_f32_16x16x32_bf16 v[86:89], v[156:159], v[216:219], v[86:89]
	v_mfma_f32_16x16x32_bf16 v[78:81], v[166:169], v[216:219], v[78:81]
	v_mfma_f32_16x16x32_bf16 v[62:65], v[156:159], v[224:227], v[62:65]
	v_mfma_f32_16x16x32_bf16 v[54:57], v[166:169], v[224:227], v[54:57]
	v_mfma_f32_16x16x32_bf16 v[118:121], v[162:165], v[204:207], v[118:121]
	v_mfma_f32_16x16x32_bf16 v[110:113], v[170:173], v[204:207], v[110:113]
	v_mfma_f32_16x16x32_bf16 v[102:105], v[162:165], v[212:215], v[102:105]
	v_mfma_f32_16x16x32_bf16 v[94:97], v[170:173], v[212:215], v[94:97]
	v_mfma_f32_16x16x32_bf16 v[86:89], v[162:165], v[220:223], v[86:89]
	v_mfma_f32_16x16x32_bf16 v[78:81], v[170:173], v[220:223], v[78:81]
	v_mfma_f32_16x16x32_bf16 v[62:65], v[162:165], v[228:231], v[62:65]
	v_mfma_f32_16x16x32_bf16 v[54:57], v[170:173], v[228:231], v[54:57]
	v_mfma_f32_16x16x32_bf16 v[126:129], v[174:177], v[200:203], v[126:129]
	v_mfma_f32_16x16x32_bf16 v[122:125], v[182:185], v[200:203], v[122:125]
	v_mfma_f32_16x16x32_bf16 v[114:117], v[174:177], v[208:211], v[114:117]
	v_mfma_f32_16x16x32_bf16 v[106:109], v[182:185], v[208:211], v[106:109]
	v_mfma_f32_16x16x32_bf16 v[98:101], v[174:177], v[216:219], v[98:101]
	v_mfma_f32_16x16x32_bf16 v[90:93], v[182:185], v[216:219], v[90:93]
	v_mfma_f32_16x16x32_bf16 v[82:85], v[174:177], v[224:227], v[82:85]
	v_mfma_f32_16x16x32_bf16 v[70:73], v[182:185], v[224:227], v[70:73]
	v_mfma_f32_16x16x32_bf16 v[126:129], v[178:181], v[204:207], v[126:129]
	v_mfma_f32_16x16x32_bf16 v[122:125], v[192:195], v[204:207], v[122:125]
	v_mfma_f32_16x16x32_bf16 v[114:117], v[178:181], v[212:215], v[114:117]
	v_mfma_f32_16x16x32_bf16 v[106:109], v[192:195], v[212:215], v[106:109]
	v_mfma_f32_16x16x32_bf16 v[98:101], v[178:181], v[220:223], v[98:101]
	v_mfma_f32_16x16x32_bf16 v[90:93], v[192:195], v[220:223], v[90:93]
	s_setprio 2
	s_barrier
	v_mfma_f32_16x16x32_bf16 v[82:85], v[178:181], v[228:231], v[82:85]
	v_mfma_f32_16x16x32_bf16 v[70:73], v[192:195], v[228:231], v[70:73]
	s_setprio 0
	s_add_u32 s30, s62, 0x8000
	s_addc_u32 s31, s63, 0
	s_add_i32 s64, s45, s5
	s_mov_b32 m0, s64
	ds_read_b128 v[200:203], v155 offset:49152
	ds_read_b128 v[204:207], v155 offset:50176
	ds_read_b128 v[208:211], v155 offset:51200
	ds_read_b128 v[212:215], v155 offset:52224
	ds_read_b128 v[216:219], v155 offset:53248
	ds_read_b128 v[220:223], v155 offset:54272
	ds_read_b128 v[224:227], v155 offset:55296
	ds_read_b128 v[228:231], v155 offset:56320
	global_load_lds_dwordx4 v134, s[30:31] sc1
	s_add_i32 m0, s64, 0x2000
	s_nop 0
	global_load_lds_dwordx4 v136, s[30:31] sc1
	s_add_u32 s30, s62, 0xc000
	s_addc_u32 s31, s63, 0
	s_add_i32 s62, s46, s5
	s_mov_b32 m0, s62
	s_nop 0
	global_load_lds_dwordx4 v134, s[30:31] sc1
	s_add_i32 m0, s62, 0x2000
	s_nop 0
	global_load_lds_dwordx4 v136, s[30:31] sc1
	s_mov_b32 m0, s40
	s_nop 0
	global_load_lds_dwordx4 v132, s[56:57] sc1
	s_mov_b32 m0, s41
	s_nop 0
	global_load_lds_dwordx4 v130, s[56:57] sc1
	s_waitcnt vmcnt(8)
	s_waitcnt lgkmcnt(0)
	s_setprio 1
	s_barrier
	v_mfma_f32_16x16x32_bf16 v[58:61], v[156:159], v[200:203], v[58:61]
	v_mfma_f32_16x16x32_bf16 v[46:49], v[166:169], v[200:203], v[46:49]
	v_mfma_f32_16x16x32_bf16 v[38:41], v[156:159], v[208:211], v[38:41]
	v_mfma_f32_16x16x32_bf16 v[30:33], v[166:169], v[208:211], v[30:33]
	v_mfma_f32_16x16x32_bf16 v[22:25], v[156:159], v[216:219], v[22:25]
	v_mfma_f32_16x16x32_bf16 v[14:17], v[166:169], v[216:219], v[14:17]
	v_mfma_f32_16x16x32_bf16 v[6:9], v[156:159], v[224:227], v[6:9]
	v_mfma_f32_16x16x32_bf16 v[2:5], v[166:169], v[224:227], v[2:5]
	v_mfma_f32_16x16x32_bf16 v[58:61], v[162:165], v[204:207], v[58:61]
	v_mfma_f32_16x16x32_bf16 v[46:49], v[170:173], v[204:207], v[46:49]
	v_mfma_f32_16x16x32_bf16 v[38:41], v[162:165], v[212:215], v[38:41]
	v_mfma_f32_16x16x32_bf16 v[30:33], v[170:173], v[212:215], v[30:33]
	v_mfma_f32_16x16x32_bf16 v[22:25], v[162:165], v[220:223], v[22:25]
	v_mfma_f32_16x16x32_bf16 v[14:17], v[170:173], v[220:223], v[14:17]
	v_mfma_f32_16x16x32_bf16 v[6:9], v[162:165], v[228:231], v[6:9]
	v_mfma_f32_16x16x32_bf16 v[2:5], v[170:173], v[228:231], v[2:5]
	v_mfma_f32_16x16x32_bf16 v[74:77], v[174:177], v[200:203], v[74:77]
	v_mfma_f32_16x16x32_bf16 v[66:69], v[182:185], v[200:203], v[66:69]
	v_mfma_f32_16x16x32_bf16 v[50:53], v[174:177], v[208:211], v[50:53]
	v_mfma_f32_16x16x32_bf16 v[42:45], v[182:185], v[208:211], v[42:45]
	v_mfma_f32_16x16x32_bf16 v[34:37], v[174:177], v[216:219], v[34:37]
	v_mfma_f32_16x16x32_bf16 v[26:29], v[182:185], v[216:219], v[26:29]
	v_mfma_f32_16x16x32_bf16 v[18:21], v[174:177], v[224:227], v[18:21]
	v_mfma_f32_16x16x32_bf16 v[10:13], v[182:185], v[224:227], v[10:13]
	v_mfma_f32_16x16x32_bf16 v[74:77], v[178:181], v[204:207], v[74:77]
	v_mfma_f32_16x16x32_bf16 v[66:69], v[192:195], v[204:207], v[66:69]
	v_mfma_f32_16x16x32_bf16 v[50:53], v[178:181], v[212:215], v[50:53]
	v_mfma_f32_16x16x32_bf16 v[42:45], v[192:195], v[212:215], v[42:45]
	v_mfma_f32_16x16x32_bf16 v[34:37], v[178:181], v[220:223], v[34:37]
	v_mfma_f32_16x16x32_bf16 v[26:29], v[192:195], v[220:223], v[26:29]
	s_setprio 2
	s_barrier
	v_mfma_f32_16x16x32_bf16 v[18:21], v[178:181], v[228:231], v[18:21]
	v_mfma_f32_16x16x32_bf16 v[10:13], v[192:195], v[228:231], v[10:13]
	s_setprio 0
	s_add_i32 s67, s67, 2
	s_add_u32 s61, s61, 0x10000
	s_addc_u32 s66, s66, 0
	s_cmp_gt_u32 s67, 13
	s_mov_b64 s[30:31], s[52:53]
	s_cbranch_scc0 .LBB0_268
	s_cmp_eq_u32 s49, s59
	s_cbranch_scc1 .Lemb0_last
	s_mov_b32 s98, s49
	s_mov_b32 s49, s35
	s_add_i32 s35, s35, 1
	s_cmp_lt_u32 s35, s15
	s_mov_b64 s[30:31], s[28:29]
	s_mov_b32 s28, s48
	s_cselect_b64 s[54:55], -1, 0
	s_add_i32 s48, s35, s4
	s_mov_b64 s[52:53], s[6:7]
	s_and_b64 s[6:7], s[54:55], exec
	s_cselect_b32 s6, s48, s28
	s_cselect_b32 s28, s58, s58
	s_ashr_i32 s29, s28, 31
	s_lshl_b64 s[28:29], s[28:29], 19
	s_add_u32 s28, s60, s28
	s_addc_u32 s29, s33, s29
	s_and_b64 s[50:51], s[54:55], exec
	s_cselect_b32 s50, s29, s31
	s_cselect_b32 s51, s28, s30
	s_ashr_i32 s7, s6, 31
	s_lshl_b64 s[6:7], s[6:7], 19
	s_add_u32 s6, s86, s6
	s_addc_u32 s7, s87, s7
	s_and_b64 s[54:55], s[54:55], exec
	s_cselect_b32 s54, s7, s53
	s_cselect_b32 s55, s6, s52
	s_add_u32 s61, s52, 0x10000
	s_addc_u32 s66, s53, 0
	s_mov_b32 s67, -2
	v_add_u32_e32 v160, s43, v1
	ds_read_b128 v[156:159], v160
	ds_read_b128 v[162:165], v160 offset:1024
	ds_read_b128 v[166:169], v160 offset:2048
	ds_read_b128 v[170:173], v160 offset:3072
	v_add_u32_e32 v160, s44, v1
	ds_read_b128 v[174:177], v160
	ds_read_b128 v[178:181], v160 offset:1024
	ds_read_b128 v[182:185], v160 offset:2048
	ds_read_b128 v[192:195], v160 offset:3072
	s_add_u32 s52, s30, 0x10000
	s_addc_u32 s53, s31, 0
	s_cmp_eq_u32 s67, 12
	s_cselect_b32 s64, s51, s52
	s_cselect_b32 s65, s50, s53
	s_cselect_b32 s62, s55, s61
	s_cselect_b32 s63, s54, s66
	s_add_u32 s56, s64, 0x8000
	s_addc_u32 s57, s65, 0
	s_add_i32 m0, s36, 0xc000
	ds_read_b128 v[200:203], v155
	ds_read_b128 v[204:207], v155 offset:1024
	ds_read_b128 v[208:211], v155 offset:2048
	ds_read_b128 v[212:215], v155 offset:3072
	ds_read_b128 v[216:219], v155 offset:4096
	ds_read_b128 v[220:223], v155 offset:5120
	ds_read_b128 v[224:227], v155 offset:6144
	ds_read_b128 v[228:231], v155 offset:7168
	v_lshl_add_u32 v199, s98, 10, v154
	ds_read_b32 v186, v199
	ds_read_b32 v187, v199 offset:64
	ds_read_b32 v196, v199 offset:128
	ds_read_b32 v197, v199 offset:192
	global_load_lds_dwordx4 v146, s[30:31] sc1
	s_add_i32 m0, s36, 0xe000
	s_nop 0
	global_load_lds_dwordx4 v148, s[30:31] sc1
	s_waitcnt vmcnt(8)
	s_waitcnt lgkmcnt(0)
	s_setprio 1
	s_barrier
	s_add_i32 s99, s98, s4
	s_lshl_b32 s99, s99, 15
	s_or_b32 s99, s99, s47
	s_and_b32 s99, s99, 0xffffc000
	s_add_i32 s100, s99, s42
	v_mul_f32_e32 v248, 0xbfb8aa3b, v186
	v_mul_f32_e32 v249, v186, v186
	v_rcp_f32_e32 v250, v249
	v_mul_f32_e32 v232, v118, v248
	v_mul_f32_e32 v233, v119, v248
	v_mul_f32_e32 v234, v120, v248
	v_mul_f32_e32 v235, v121, v248
	v_mul_f32_e32 v236, v110, v248
	v_mul_f32_e32 v237, v111, v248
	v_mul_f32_e32 v238, v112, v248
	v_mul_f32_e32 v239, v113, v248
	v_mul_f32_e32 v240, v118, v126
	v_mul_f32_e32 v241, v119, v127
	v_mul_f32_e32 v242, v120, v128
	v_mul_f32_e32 v243, v121, v129
	v_mul_f32_e32 v244, v110, v122
	v_mul_f32_e32 v245, v111, v123
	v_mul_f32_e32 v246, v112, v124
	v_mul_f32_e32 v247, v113, v125
	v_exp_f32_e32 v232, v232
	v_exp_f32_e32 v233, v233
	v_exp_f32_e32 v234, v234
	v_exp_f32_e32 v235, v235
	v_mfma_f32_16x16x32_bf16 v[118:121], v[156:159], v[200:203], 0
	v_exp_f32_e32 v236, v236
	v_exp_f32_e32 v237, v237
	v_exp_f32_e32 v238, v238
	v_exp_f32_e32 v239, v239
	v_mfma_f32_16x16x32_bf16 v[110:113], v[166:169], v[200:203], 0
	v_fma_f32 v232, v232, v250, v250
	v_fma_f32 v233, v233, v250, v250
	v_fma_f32 v234, v234, v250, v250
	v_fma_f32 v235, v235, v250, v250
	v_mfma_f32_16x16x32_bf16 v[126:129], v[174:177], v[200:203], 0
	v_fma_f32 v236, v236, v250, v250
	v_fma_f32 v237, v237, v250, v250
	v_fma_f32 v238, v238, v250, v250
	v_fma_f32 v239, v239, v250, v250
	v_mfma_f32_16x16x32_bf16 v[122:125], v[182:185], v[200:203], 0
	v_rcp_f32_e32 v232, v232
	v_rcp_f32_e32 v233, v233
	v_rcp_f32_e32 v234, v234
	v_rcp_f32_e32 v235, v235
	v_mfma_f32_16x16x32_bf16 v[118:121], v[162:165], v[204:207], v[118:121]
	v_rcp_f32_e32 v236, v236
	v_rcp_f32_e32 v237, v237
	v_rcp_f32_e32 v238, v238
	v_rcp_f32_e32 v239, v239
	v_mfma_f32_16x16x32_bf16 v[110:113], v[170:173], v[204:207], v[110:113]
	v_or_b32_e32 v251, s100, v139
	v_lshlrev_b32_e32 v251, 1, v251
	v_mul_f32_e32 v240, v240, v232
	v_mul_f32_e32 v241, v241, v233
	v_mfma_f32_16x16x32_bf16 v[126:129], v[178:181], v[204:207], v[126:129]
	v_mul_f32_e32 v242, v242, v234
	v_mul_f32_e32 v243, v243, v235
	v_mul_f32_e32 v244, v244, v236
	v_mul_f32_e32 v245, v245, v237
	v_mfma_f32_16x16x32_bf16 v[122:125], v[192:195], v[204:207], v[122:125]
	v_mul_f32_e32 v246, v246, v238
	v_mul_f32_e32 v247, v247, v239
	v_cvt_pk_bf16_f32 v232, v240, v241
	v_cvt_pk_bf16_f32 v233, v242, v243
	v_cvt_pk_bf16_f32 v234, v244, v245
	v_cvt_pk_bf16_f32 v235, v246, v247
	buffer_store_dwordx4 v[232:235], v251, s[72:75], 0 offen sc1
	v_mul_f32_e32 v248, 0xbfb8aa3b, v187
	v_mul_f32_e32 v249, v187, v187
	v_rcp_f32_e32 v250, v249
	v_mul_f32_e32 v232, v102, v248
	v_mul_f32_e32 v233, v103, v248
	v_mul_f32_e32 v234, v104, v248
	v_mul_f32_e32 v235, v105, v248
	v_mul_f32_e32 v236, v94, v248
	v_mul_f32_e32 v237, v95, v248
	v_mul_f32_e32 v238, v96, v248
	v_mul_f32_e32 v239, v97, v248
	v_mul_f32_e32 v240, v102, v114
	v_mul_f32_e32 v241, v103, v115
	v_mul_f32_e32 v242, v104, v116
	v_mul_f32_e32 v243, v105, v117
	v_mul_f32_e32 v244, v94, v106
	v_mul_f32_e32 v245, v95, v107
	v_mul_f32_e32 v246, v96, v108
	v_mul_f32_e32 v247, v97, v109
	v_exp_f32_e32 v232, v232
	v_exp_f32_e32 v233, v233
	v_exp_f32_e32 v234, v234
	v_exp_f32_e32 v235, v235
	v_mfma_f32_16x16x32_bf16 v[102:105], v[156:159], v[208:211], 0
	v_exp_f32_e32 v236, v236
	v_exp_f32_e32 v237, v237
	v_exp_f32_e32 v238, v238
	v_exp_f32_e32 v239, v239
	v_mfma_f32_16x16x32_bf16 v[94:97], v[166:169], v[208:211], 0
	v_fma_f32 v232, v232, v250, v250
	v_fma_f32 v233, v233, v250, v250
	v_fma_f32 v234, v234, v250, v250
	v_fma_f32 v235, v235, v250, v250
	v_mfma_f32_16x16x32_bf16 v[114:117], v[174:177], v[208:211], 0
	v_fma_f32 v236, v236, v250, v250
	v_fma_f32 v237, v237, v250, v250
	v_fma_f32 v238, v238, v250, v250
	v_fma_f32 v239, v239, v250, v250
	v_mfma_f32_16x16x32_bf16 v[106:109], v[182:185], v[208:211], 0
	v_rcp_f32_e32 v232, v232
	v_rcp_f32_e32 v233, v233
	v_rcp_f32_e32 v234, v234
	v_rcp_f32_e32 v235, v235
	v_mfma_f32_16x16x32_bf16 v[102:105], v[162:165], v[212:215], v[102:105]
	v_rcp_f32_e32 v236, v236
	v_rcp_f32_e32 v237, v237
	v_rcp_f32_e32 v238, v238
	v_rcp_f32_e32 v239, v239
	v_mfma_f32_16x16x32_bf16 v[94:97], v[170:173], v[212:215], v[94:97]
	v_or_b32_e32 v251, s100, v141
	v_lshlrev_b32_e32 v251, 1, v251
	v_mul_f32_e32 v240, v240, v232
	v_mul_f32_e32 v241, v241, v233
	v_mfma_f32_16x16x32_bf16 v[114:117], v[178:181], v[212:215], v[114:117]
	v_mul_f32_e32 v242, v242, v234
	v_mul_f32_e32 v243, v243, v235
	v_mul_f32_e32 v244, v244, v236
	v_mul_f32_e32 v245, v245, v237
	v_mfma_f32_16x16x32_bf16 v[106:109], v[192:195], v[212:215], v[106:109]
	v_mul_f32_e32 v246, v246, v238
	v_mul_f32_e32 v247, v247, v239
	v_cvt_pk_bf16_f32 v232, v240, v241
	v_cvt_pk_bf16_f32 v233, v242, v243
	v_cvt_pk_bf16_f32 v234, v244, v245
	v_cvt_pk_bf16_f32 v235, v246, v247
	buffer_store_dwordx4 v[232:235], v251, s[72:75], 0 offen sc1
	v_mul_f32_e32 v248, 0xbfb8aa3b, v196
	v_mul_f32_e32 v249, v196, v196
	v_rcp_f32_e32 v250, v249
	v_mul_f32_e32 v232, v86, v248
	v_mul_f32_e32 v233, v87, v248
	v_mul_f32_e32 v234, v88, v248
	v_mul_f32_e32 v235, v89, v248
	v_mul_f32_e32 v236, v78, v248
	v_mul_f32_e32 v237, v79, v248
	v_mul_f32_e32 v238, v80, v248
	v_mul_f32_e32 v239, v81, v248
	v_mul_f32_e32 v240, v86, v98
	v_mul_f32_e32 v241, v87, v99
	v_mul_f32_e32 v242, v88, v100
	v_mul_f32_e32 v243, v89, v101
	v_mul_f32_e32 v244, v78, v90
	v_mul_f32_e32 v245, v79, v91
	v_mul_f32_e32 v246, v80, v92
	v_mul_f32_e32 v247, v81, v93
	v_exp_f32_e32 v232, v232
	v_exp_f32_e32 v233, v233
	v_exp_f32_e32 v234, v234
	v_exp_f32_e32 v235, v235
	v_mfma_f32_16x16x32_bf16 v[86:89], v[156:159], v[216:219], 0
	v_exp_f32_e32 v236, v236
	v_exp_f32_e32 v237, v237
	v_exp_f32_e32 v238, v238
	v_exp_f32_e32 v239, v239
	v_mfma_f32_16x16x32_bf16 v[78:81], v[166:169], v[216:219], 0
	v_fma_f32 v232, v232, v250, v250
	v_fma_f32 v233, v233, v250, v250
	v_fma_f32 v234, v234, v250, v250
	v_fma_f32 v235, v235, v250, v250
	v_mfma_f32_16x16x32_bf16 v[98:101], v[174:177], v[216:219], 0
	v_fma_f32 v236, v236, v250, v250
	v_fma_f32 v237, v237, v250, v250
	v_fma_f32 v238, v238, v250, v250
	v_fma_f32 v239, v239, v250, v250
	v_mfma_f32_16x16x32_bf16 v[90:93], v[182:185], v[216:219], 0
	v_rcp_f32_e32 v232, v232
	v_rcp_f32_e32 v233, v233
	v_rcp_f32_e32 v234, v234
	v_rcp_f32_e32 v235, v235
	v_mfma_f32_16x16x32_bf16 v[86:89], v[162:165], v[220:223], v[86:89]
	v_rcp_f32_e32 v236, v236
	v_rcp_f32_e32 v237, v237
	v_rcp_f32_e32 v238, v238
	v_rcp_f32_e32 v239, v239
	v_mfma_f32_16x16x32_bf16 v[78:81], v[170:173], v[220:223], v[78:81]
	v_or_b32_e32 v251, s100, v143
	v_lshlrev_b32_e32 v251, 1, v251
	v_mul_f32_e32 v240, v240, v232
	v_mul_f32_e32 v241, v241, v233
	v_mfma_f32_16x16x32_bf16 v[98:101], v[178:181], v[220:223], v[98:101]
	v_mul_f32_e32 v242, v242, v234
	v_mul_f32_e32 v243, v243, v235
	v_mul_f32_e32 v244, v244, v236
	v_mul_f32_e32 v245, v245, v237
	v_mfma_f32_16x16x32_bf16 v[90:93], v[192:195], v[220:223], v[90:93]
	v_mul_f32_e32 v246, v246, v238
	v_mul_f32_e32 v247, v247, v239
	v_cvt_pk_bf16_f32 v232, v240, v241
	v_cvt_pk_bf16_f32 v233, v242, v243
	v_cvt_pk_bf16_f32 v234, v244, v245
	v_cvt_pk_bf16_f32 v235, v246, v247
	buffer_store_dwordx4 v[232:235], v251, s[72:75], 0 offen sc1
	v_mul_f32_e32 v248, 0xbfb8aa3b, v197
	v_mul_f32_e32 v249, v197, v197
	v_rcp_f32_e32 v250, v249
	v_mul_f32_e32 v232, v62, v248
	v_mul_f32_e32 v233, v63, v248
	v_mul_f32_e32 v234, v64, v248
	v_mul_f32_e32 v235, v65, v248
	v_mul_f32_e32 v236, v54, v248
	v_mul_f32_e32 v237, v55, v248
	v_mul_f32_e32 v238, v56, v248
	v_mul_f32_e32 v239, v57, v248
	v_mul_f32_e32 v240, v62, v82
	v_mul_f32_e32 v241, v63, v83
	v_mul_f32_e32 v242, v64, v84
	v_mul_f32_e32 v243, v65, v85
	v_mul_f32_e32 v244, v54, v70
	v_mul_f32_e32 v245, v55, v71
	v_mul_f32_e32 v246, v56, v72
	v_mul_f32_e32 v247, v57, v73
	v_exp_f32_e32 v232, v232
	v_exp_f32_e32 v233, v233
	v_exp_f32_e32 v234, v234
	v_exp_f32_e32 v235, v235
	v_mfma_f32_16x16x32_bf16 v[62:65], v[156:159], v[224:227], 0
	v_exp_f32_e32 v236, v236
	v_exp_f32_e32 v237, v237
	v_exp_f32_e32 v238, v238
	v_exp_f32_e32 v239, v239
	v_mfma_f32_16x16x32_bf16 v[54:57], v[166:169], v[224:227], 0
	v_fma_f32 v232, v232, v250, v250
	v_fma_f32 v233, v233, v250, v250
	v_fma_f32 v234, v234, v250, v250
	v_fma_f32 v235, v235, v250, v250
	v_mfma_f32_16x16x32_bf16 v[82:85], v[174:177], v[224:227], 0
	v_fma_f32 v236, v236, v250, v250
	v_fma_f32 v237, v237, v250, v250
	v_fma_f32 v238, v238, v250, v250
	v_fma_f32 v239, v239, v250, v250
	v_mfma_f32_16x16x32_bf16 v[70:73], v[182:185], v[224:227], 0
	v_rcp_f32_e32 v232, v232
	v_rcp_f32_e32 v233, v233
	v_rcp_f32_e32 v234, v234
	v_rcp_f32_e32 v235, v235
	v_mfma_f32_16x16x32_bf16 v[62:65], v[162:165], v[228:231], v[62:65]
	v_rcp_f32_e32 v236, v236
	v_rcp_f32_e32 v237, v237
	v_rcp_f32_e32 v238, v238
	v_rcp_f32_e32 v239, v239
	v_mfma_f32_16x16x32_bf16 v[54:57], v[170:173], v[228:231], v[54:57]
	v_or_b32_e32 v251, s100, v145
	v_lshlrev_b32_e32 v251, 1, v251
	v_mul_f32_e32 v240, v240, v232
	v_mul_f32_e32 v241, v241, v233
	v_mul_f32_e32 v242, v242, v234
	v_mul_f32_e32 v243, v243, v235
	v_mul_f32_e32 v244, v244, v236
	v_mul_f32_e32 v245, v245, v237
	v_mul_f32_e32 v246, v246, v238
	v_mul_f32_e32 v247, v247, v239
	v_cvt_pk_bf16_f32 v232, v240, v241
	v_cvt_pk_bf16_f32 v233, v242, v243
	v_cvt_pk_bf16_f32 v234, v244, v245
	v_cvt_pk_bf16_f32 v235, v246, v247
	buffer_store_dwordx4 v[232:235], v251, s[72:75], 0 offen sc1
	s_setprio 2
	s_barrier
	v_mfma_f32_16x16x32_bf16 v[82:85], v[178:181], v[228:231], v[82:85]
	v_mfma_f32_16x16x32_bf16 v[70:73], v[192:195], v[228:231], v[70:73]
	s_setprio 0
	s_add_i32 s30, s43, s5
	s_mov_b32 m0, s30
	ds_read_b128 v[200:203], v155 offset:16384
	ds_read_b128 v[204:207], v155 offset:17408
	ds_read_b128 v[208:211], v155 offset:18432
	ds_read_b128 v[212:215], v155 offset:19456
	ds_read_b128 v[216:219], v155 offset:20480
	ds_read_b128 v[220:223], v155 offset:21504
	ds_read_b128 v[224:227], v155 offset:22528
	ds_read_b128 v[228:231], v155 offset:23552
	ds_read_b32 v186, v199 offset:512
	ds_read_b32 v187, v199 offset:576
	ds_read_b32 v196, v199 offset:640
	ds_read_b32 v197, v199 offset:704
	global_load_lds_dwordx4 v134, s[62:63] sc1
	s_add_i32 m0, s30, 0x2000
	s_add_u32 s30, s62, 0x4000
	s_addc_u32 s31, s63, 0
	s_add_i32 s69, s44, s5
	global_load_lds_dwordx4 v136, s[62:63] sc1
	s_mov_b32 m0, s69
	s_nop 0
	global_load_lds_dwordx4 v134, s[30:31] sc1
	s_add_i32 m0, s69, 0x2000
	s_nop 0
	global_load_lds_dwordx4 v136, s[30:31] sc1
	s_mov_b32 m0, s36
	s_nop 0
	global_load_lds_dwordx4 v132, s[64:65] sc1
	s_mov_b32 m0, s37
	s_nop 0
	global_load_lds_dwordx4 v130, s[64:65] sc1
	s_waitcnt vmcnt(12)
	s_waitcnt lgkmcnt(0)
	s_setprio 1
	s_barrier
	v_mul_f32_e32 v248, 0xbfb8aa3b, v186
	v_mul_f32_e32 v249, v186, v186
	v_rcp_f32_e32 v250, v249
	v_mul_f32_e32 v232, v58, v248
	v_mul_f32_e32 v233, v59, v248
	v_mul_f32_e32 v234, v60, v248
	v_mul_f32_e32 v235, v61, v248
	v_mul_f32_e32 v236, v46, v248
	v_mul_f32_e32 v237, v47, v248
	v_mul_f32_e32 v238, v48, v248
	v_mul_f32_e32 v239, v49, v248
	v_mul_f32_e32 v240, v58, v74
	v_mul_f32_e32 v241, v59, v75
	v_mul_f32_e32 v242, v60, v76
	v_mul_f32_e32 v243, v61, v77
	v_mul_f32_e32 v244, v46, v66
	v_mul_f32_e32 v245, v47, v67
	v_mul_f32_e32 v246, v48, v68
	v_mul_f32_e32 v247, v49, v69
	v_exp_f32_e32 v232, v232
	v_exp_f32_e32 v233, v233
	v_exp_f32_e32 v234, v234
	v_exp_f32_e32 v235, v235
	v_mfma_f32_16x16x32_bf16 v[58:61], v[156:159], v[200:203], 0
	v_exp_f32_e32 v236, v236
	v_exp_f32_e32 v237, v237
	v_exp_f32_e32 v238, v238
	v_exp_f32_e32 v239, v239
	v_mfma_f32_16x16x32_bf16 v[46:49], v[166:169], v[200:203], 0
	v_fma_f32 v232, v232, v250, v250
	v_fma_f32 v233, v233, v250, v250
	v_fma_f32 v234, v234, v250, v250
	v_fma_f32 v235, v235, v250, v250
	v_mfma_f32_16x16x32_bf16 v[74:77], v[174:177], v[200:203], 0
	v_fma_f32 v236, v236, v250, v250
	v_fma_f32 v237, v237, v250, v250
	v_fma_f32 v238, v238, v250, v250
	v_fma_f32 v239, v239, v250, v250
	v_mfma_f32_16x16x32_bf16 v[66:69], v[182:185], v[200:203], 0
	v_rcp_f32_e32 v232, v232
	v_rcp_f32_e32 v233, v233
	v_rcp_f32_e32 v234, v234
	v_rcp_f32_e32 v235, v235
	v_mfma_f32_16x16x32_bf16 v[58:61], v[162:165], v[204:207], v[58:61]
	v_rcp_f32_e32 v236, v236
	v_rcp_f32_e32 v237, v237
	v_rcp_f32_e32 v238, v238
	v_rcp_f32_e32 v239, v239
	v_mfma_f32_16x16x32_bf16 v[46:49], v[170:173], v[204:207], v[46:49]
	v_add_u32_e32 v251, s99, v138
	v_or_b32_e32 v251, v251, v150
	v_lshlrev_b32_e32 v251, 1, v251
	v_mul_f32_e32 v240, v240, v232
	v_mfma_f32_16x16x32_bf16 v[74:77], v[178:181], v[204:207], v[74:77]
	v_mul_f32_e32 v241, v241, v233
	v_mul_f32_e32 v242, v242, v234
	v_mul_f32_e32 v243, v243, v235
	v_mul_f32_e32 v244, v244, v236
	v_mfma_f32_16x16x32_bf16 v[66:69], v[192:195], v[204:207], v[66:69]
	v_mul_f32_e32 v245, v245, v237
	v_mul_f32_e32 v246, v246, v238
	v_mul_f32_e32 v247, v247, v239
	v_cvt_pk_bf16_f32 v232, v240, v241
	v_cvt_pk_bf16_f32 v233, v242, v243
	v_cvt_pk_bf16_f32 v234, v244, v245
	v_cvt_pk_bf16_f32 v235, v246, v247
	buffer_store_dwordx4 v[232:235], v251, s[72:75], 0 offen sc1
	v_mul_f32_e32 v248, 0xbfb8aa3b, v187
	v_mul_f32_e32 v249, v187, v187
	v_rcp_f32_e32 v250, v249
	v_mul_f32_e32 v232, v38, v248
	v_mul_f32_e32 v233, v39, v248
	v_mul_f32_e32 v234, v40, v248
	v_mul_f32_e32 v235, v41, v248
	v_mul_f32_e32 v236, v30, v248
	v_mul_f32_e32 v237, v31, v248
	v_mul_f32_e32 v238, v32, v248
	v_mul_f32_e32 v239, v33, v248
	v_mul_f32_e32 v240, v38, v50
	v_mul_f32_e32 v241, v39, v51
	v_mul_f32_e32 v242, v40, v52
	v_mul_f32_e32 v243, v41, v53
	v_mul_f32_e32 v244, v30, v42
	v_mul_f32_e32 v245, v31, v43
	v_mul_f32_e32 v246, v32, v44
	v_mul_f32_e32 v247, v33, v45
	v_exp_f32_e32 v232, v232
	v_exp_f32_e32 v233, v233
	v_exp_f32_e32 v234, v234
	v_exp_f32_e32 v235, v235
	v_mfma_f32_16x16x32_bf16 v[38:41], v[156:159], v[208:211], 0
	v_exp_f32_e32 v236, v236
	v_exp_f32_e32 v237, v237
	v_exp_f32_e32 v238, v238
	v_exp_f32_e32 v239, v239
	v_mfma_f32_16x16x32_bf16 v[30:33], v[166:169], v[208:211], 0
	v_fma_f32 v232, v232, v250, v250
	v_fma_f32 v233, v233, v250, v250
	v_fma_f32 v234, v234, v250, v250
	v_fma_f32 v235, v235, v250, v250
	v_mfma_f32_16x16x32_bf16 v[50:53], v[174:177], v[208:211], 0
	v_fma_f32 v236, v236, v250, v250
	v_fma_f32 v237, v237, v250, v250
	v_fma_f32 v238, v238, v250, v250
	v_fma_f32 v239, v239, v250, v250
	v_mfma_f32_16x16x32_bf16 v[42:45], v[182:185], v[208:211], 0
	v_rcp_f32_e32 v232, v232
	v_rcp_f32_e32 v233, v233
	v_rcp_f32_e32 v234, v234
	v_rcp_f32_e32 v235, v235
	v_mfma_f32_16x16x32_bf16 v[38:41], v[162:165], v[212:215], v[38:41]
	v_rcp_f32_e32 v236, v236
	v_rcp_f32_e32 v237, v237
	v_rcp_f32_e32 v238, v238
	v_rcp_f32_e32 v239, v239
	v_mfma_f32_16x16x32_bf16 v[30:33], v[170:173], v[212:215], v[30:33]
	v_add_u32_e32 v251, s99, v140
	v_or_b32_e32 v251, v251, v151
	v_lshlrev_b32_e32 v251, 1, v251
	v_mul_f32_e32 v240, v240, v232
	v_mfma_f32_16x16x32_bf16 v[50:53], v[178:181], v[212:215], v[50:53]
	v_mul_f32_e32 v241, v241, v233
	v_mul_f32_e32 v242, v242, v234
	v_mul_f32_e32 v243, v243, v235
	v_mul_f32_e32 v244, v244, v236
	v_mfma_f32_16x16x32_bf16 v[42:45], v[192:195], v[212:215], v[42:45]
	v_mul_f32_e32 v245, v245, v237
	v_mul_f32_e32 v246, v246, v238
	v_mul_f32_e32 v247, v247, v239
	v_cvt_pk_bf16_f32 v232, v240, v241
	v_cvt_pk_bf16_f32 v233, v242, v243
	v_cvt_pk_bf16_f32 v234, v244, v245
	v_cvt_pk_bf16_f32 v235, v246, v247
	buffer_store_dwordx4 v[232:235], v251, s[72:75], 0 offen sc1
	v_mul_f32_e32 v248, 0xbfb8aa3b, v196
	v_mul_f32_e32 v249, v196, v196
	v_rcp_f32_e32 v250, v249
	v_mul_f32_e32 v232, v22, v248
	v_mul_f32_e32 v233, v23, v248
	v_mul_f32_e32 v234, v24, v248
	v_mul_f32_e32 v235, v25, v248
	v_mul_f32_e32 v236, v14, v248
	v_mul_f32_e32 v237, v15, v248
	v_mul_f32_e32 v238, v16, v248
	v_mul_f32_e32 v239, v17, v248
	v_mul_f32_e32 v240, v22, v34
	v_mul_f32_e32 v241, v23, v35
	v_mul_f32_e32 v242, v24, v36
	v_mul_f32_e32 v243, v25, v37
	v_mul_f32_e32 v244, v14, v26
	v_mul_f32_e32 v245, v15, v27
	v_mul_f32_e32 v246, v16, v28
	v_mul_f32_e32 v247, v17, v29
	v_exp_f32_e32 v232, v232
	v_exp_f32_e32 v233, v233
	v_exp_f32_e32 v234, v234
	v_exp_f32_e32 v235, v235
	v_mfma_f32_16x16x32_bf16 v[22:25], v[156:159], v[216:219], 0
	v_exp_f32_e32 v236, v236
	v_exp_f32_e32 v237, v237
	v_exp_f32_e32 v238, v238
	v_exp_f32_e32 v239, v239
	v_mfma_f32_16x16x32_bf16 v[14:17], v[166:169], v[216:219], 0
	v_fma_f32 v232, v232, v250, v250
	v_fma_f32 v233, v233, v250, v250
	v_fma_f32 v234, v234, v250, v250
	v_fma_f32 v235, v235, v250, v250
	v_mfma_f32_16x16x32_bf16 v[34:37], v[174:177], v[216:219], 0
	v_fma_f32 v236, v236, v250, v250
	v_fma_f32 v237, v237, v250, v250
	v_fma_f32 v238, v238, v250, v250
	v_fma_f32 v239, v239, v250, v250
	v_mfma_f32_16x16x32_bf16 v[26:29], v[182:185], v[216:219], 0
	v_rcp_f32_e32 v232, v232
	v_rcp_f32_e32 v233, v233
	v_rcp_f32_e32 v234, v234
	v_rcp_f32_e32 v235, v235
	v_mfma_f32_16x16x32_bf16 v[22:25], v[162:165], v[220:223], v[22:25]
	v_rcp_f32_e32 v236, v236
	v_rcp_f32_e32 v237, v237
	v_rcp_f32_e32 v238, v238
	v_rcp_f32_e32 v239, v239
	v_mfma_f32_16x16x32_bf16 v[14:17], v[170:173], v[220:223], v[14:17]
	v_add_u32_e32 v251, s99, v142
	v_or_b32_e32 v251, v251, v152
	v_lshlrev_b32_e32 v251, 1, v251
	v_mul_f32_e32 v240, v240, v232
	v_mfma_f32_16x16x32_bf16 v[34:37], v[178:181], v[220:223], v[34:37]
	v_mul_f32_e32 v241, v241, v233
	v_mul_f32_e32 v242, v242, v234
	v_mul_f32_e32 v243, v243, v235
	v_mul_f32_e32 v244, v244, v236
	v_mfma_f32_16x16x32_bf16 v[26:29], v[192:195], v[220:223], v[26:29]
	v_mul_f32_e32 v245, v245, v237
	v_mul_f32_e32 v246, v246, v238
	v_mul_f32_e32 v247, v247, v239
	v_cvt_pk_bf16_f32 v232, v240, v241
	v_cvt_pk_bf16_f32 v233, v242, v243
	v_cvt_pk_bf16_f32 v234, v244, v245
	v_cvt_pk_bf16_f32 v235, v246, v247
	buffer_store_dwordx4 v[232:235], v251, s[72:75], 0 offen sc1
	v_mul_f32_e32 v248, 0xbfb8aa3b, v197
	v_mul_f32_e32 v249, v197, v197
	v_rcp_f32_e32 v250, v249
	v_mul_f32_e32 v232, v6, v248
	v_mul_f32_e32 v233, v7, v248
	v_mul_f32_e32 v234, v8, v248
	v_mul_f32_e32 v235, v9, v248
	v_mul_f32_e32 v236, v2, v248
	v_mul_f32_e32 v237, v3, v248
	v_mul_f32_e32 v238, v4, v248
	v_mul_f32_e32 v239, v5, v248
	v_mul_f32_e32 v240, v6, v18
	v_mul_f32_e32 v241, v7, v19
	v_mul_f32_e32 v242, v8, v20
	v_mul_f32_e32 v243, v9, v21
	v_mul_f32_e32 v244, v2, v10
	v_mul_f32_e32 v245, v3, v11
	v_mul_f32_e32 v246, v4, v12
	v_mul_f32_e32 v247, v5, v13
	v_exp_f32_e32 v232, v232
	v_exp_f32_e32 v233, v233
	v_exp_f32_e32 v234, v234
	v_exp_f32_e32 v235, v235
	v_mfma_f32_16x16x32_bf16 v[6:9], v[156:159], v[224:227], 0
	v_exp_f32_e32 v236, v236
	v_exp_f32_e32 v237, v237
	v_exp_f32_e32 v238, v238
	v_exp_f32_e32 v239, v239
	v_mfma_f32_16x16x32_bf16 v[2:5], v[166:169], v[224:227], 0
	v_fma_f32 v232, v232, v250, v250
	v_fma_f32 v233, v233, v250, v250
	v_fma_f32 v234, v234, v250, v250
	v_fma_f32 v235, v235, v250, v250
	v_mfma_f32_16x16x32_bf16 v[18:21], v[174:177], v[224:227], 0
	v_fma_f32 v236, v236, v250, v250
	v_fma_f32 v237, v237, v250, v250
	v_fma_f32 v238, v238, v250, v250
	v_fma_f32 v239, v239, v250, v250
	v_mfma_f32_16x16x32_bf16 v[10:13], v[182:185], v[224:227], 0
	v_rcp_f32_e32 v232, v232
	v_rcp_f32_e32 v233, v233
	v_rcp_f32_e32 v234, v234
	v_rcp_f32_e32 v235, v235
	v_mfma_f32_16x16x32_bf16 v[6:9], v[162:165], v[228:231], v[6:9]
	v_rcp_f32_e32 v236, v236
	v_rcp_f32_e32 v237, v237
	v_rcp_f32_e32 v238, v238
	v_rcp_f32_e32 v239, v239
	v_mfma_f32_16x16x32_bf16 v[2:5], v[170:173], v[228:231], v[2:5]
	v_add_u32_e32 v251, s99, v144
	v_or_b32_e32 v251, v251, v153
	v_lshlrev_b32_e32 v251, 1, v251
	v_mul_f32_e32 v240, v240, v232
	v_mul_f32_e32 v241, v241, v233
	v_mul_f32_e32 v242, v242, v234
	v_mul_f32_e32 v243, v243, v235
	v_mul_f32_e32 v244, v244, v236
	v_mul_f32_e32 v245, v245, v237
	v_mul_f32_e32 v246, v246, v238
	v_mul_f32_e32 v247, v247, v239
	v_cvt_pk_bf16_f32 v232, v240, v241
	v_cvt_pk_bf16_f32 v233, v242, v243
	v_cvt_pk_bf16_f32 v234, v244, v245
	v_cvt_pk_bf16_f32 v235, v246, v247
	buffer_store_dwordx4 v[232:235], v251, s[72:75], 0 offen sc1
	s_setprio 2
	s_barrier
	v_mfma_f32_16x16x32_bf16 v[18:21], v[178:181], v[228:231], v[18:21]
	v_mfma_f32_16x16x32_bf16 v[10:13], v[192:195], v[228:231], v[10:13]
	s_setprio 0
	v_add_u32_e32 v160, s45, v1
	ds_read_b128 v[156:159], v160
	ds_read_b128 v[162:165], v160 offset:1024
	ds_read_b128 v[166:169], v160 offset:2048
	ds_read_b128 v[170:173], v160 offset:3072
	v_add_u32_e32 v160, s46, v1
	ds_read_b128 v[174:177], v160
	ds_read_b128 v[178:181], v160 offset:1024
	ds_read_b128 v[182:185], v160 offset:2048
	ds_read_b128 v[192:195], v160 offset:3072
	s_add_u32 s30, s64, 0x4000
	s_addc_u32 s31, s65, 0
	s_mov_b32 m0, s38
	ds_read_b128 v[200:203], v155 offset:32768
	ds_read_b128 v[204:207], v155 offset:33792
	ds_read_b128 v[208:211], v155 offset:34816
	ds_read_b128 v[212:215], v155 offset:35840
	ds_read_b128 v[216:219], v155 offset:36864
	ds_read_b128 v[220:223], v155 offset:37888
	ds_read_b128 v[224:227], v155 offset:38912
	ds_read_b128 v[228:231], v155 offset:39936
	global_load_lds_dwordx4 v132, s[30:31] sc1
	s_mov_b32 m0, s39
	s_nop 0
	global_load_lds_dwordx4 v130, s[30:31] sc1
	s_waitcnt vmcnt(16)
	s_waitcnt lgkmcnt(0)
	s_setprio 1
	s_barrier
	v_mfma_f32_16x16x32_bf16 v[118:121], v[156:159], v[200:203], v[118:121]
	v_mfma_f32_16x16x32_bf16 v[110:113], v[166:169], v[200:203], v[110:113]
	v_mfma_f32_16x16x32_bf16 v[102:105], v[156:159], v[208:211], v[102:105]
	v_mfma_f32_16x16x32_bf16 v[94:97], v[166:169], v[208:211], v[94:97]
	v_mfma_f32_16x16x32_bf16 v[86:89], v[156:159], v[216:219], v[86:89]
	v_mfma_f32_16x16x32_bf16 v[78:81], v[166:169], v[216:219], v[78:81]
	v_mfma_f32_16x16x32_bf16 v[62:65], v[156:159], v[224:227], v[62:65]
	v_mfma_f32_16x16x32_bf16 v[54:57], v[166:169], v[224:227], v[54:57]
	v_mfma_f32_16x16x32_bf16 v[118:121], v[162:165], v[204:207], v[118:121]
	v_mfma_f32_16x16x32_bf16 v[110:113], v[170:173], v[204:207], v[110:113]
	v_mfma_f32_16x16x32_bf16 v[102:105], v[162:165], v[212:215], v[102:105]
	v_mfma_f32_16x16x32_bf16 v[94:97], v[170:173], v[212:215], v[94:97]
	v_mfma_f32_16x16x32_bf16 v[86:89], v[162:165], v[220:223], v[86:89]
	v_mfma_f32_16x16x32_bf16 v[78:81], v[170:173], v[220:223], v[78:81]
	v_mfma_f32_16x16x32_bf16 v[62:65], v[162:165], v[228:231], v[62:65]
	v_mfma_f32_16x16x32_bf16 v[54:57], v[170:173], v[228:231], v[54:57]
	v_mfma_f32_16x16x32_bf16 v[126:129], v[174:177], v[200:203], v[126:129]
	v_mfma_f32_16x16x32_bf16 v[122:125], v[182:185], v[200:203], v[122:125]
	v_mfma_f32_16x16x32_bf16 v[114:117], v[174:177], v[208:211], v[114:117]
	v_mfma_f32_16x16x32_bf16 v[106:109], v[182:185], v[208:211], v[106:109]
	v_mfma_f32_16x16x32_bf16 v[98:101], v[174:177], v[216:219], v[98:101]
	v_mfma_f32_16x16x32_bf16 v[90:93], v[182:185], v[216:219], v[90:93]
	v_mfma_f32_16x16x32_bf16 v[82:85], v[174:177], v[224:227], v[82:85]
	v_mfma_f32_16x16x32_bf16 v[70:73], v[182:185], v[224:227], v[70:73]
	v_mfma_f32_16x16x32_bf16 v[126:129], v[178:181], v[204:207], v[126:129]
	v_mfma_f32_16x16x32_bf16 v[122:125], v[192:195], v[204:207], v[122:125]
	v_mfma_f32_16x16x32_bf16 v[114:117], v[178:181], v[212:215], v[114:117]
	v_mfma_f32_16x16x32_bf16 v[106:109], v[192:195], v[212:215], v[106:109]
	v_mfma_f32_16x16x32_bf16 v[98:101], v[178:181], v[220:223], v[98:101]
	v_mfma_f32_16x16x32_bf16 v[90:93], v[192:195], v[220:223], v[90:93]
	s_setprio 2
	s_barrier
	v_mfma_f32_16x16x32_bf16 v[82:85], v[178:181], v[228:231], v[82:85]
	v_mfma_f32_16x16x32_bf16 v[70:73], v[192:195], v[228:231], v[70:73]
	s_setprio 0
	s_add_u32 s30, s62, 0x8000
	s_addc_u32 s31, s63, 0
	s_add_i32 s64, s45, s5
	s_mov_b32 m0, s64
	ds_read_b128 v[200:203], v155 offset:49152
	ds_read_b128 v[204:207], v155 offset:50176
	ds_read_b128 v[208:211], v155 offset:51200
	ds_read_b128 v[212:215], v155 offset:52224
	ds_read_b128 v[216:219], v155 offset:53248
	ds_read_b128 v[220:223], v155 offset:54272
	ds_read_b128 v[224:227], v155 offset:55296
	ds_read_b128 v[228:231], v155 offset:56320
	global_load_lds_dwordx4 v134, s[30:31] sc1
	s_add_i32 m0, s64, 0x2000
	s_nop 0
	global_load_lds_dwordx4 v136, s[30:31] sc1
	s_add_u32 s30, s62, 0xc000
	s_addc_u32 s31, s63, 0
	s_add_i32 s62, s46, s5
	s_mov_b32 m0, s62
	s_nop 0
	global_load_lds_dwordx4 v134, s[30:31] sc1
	s_add_i32 m0, s62, 0x2000
	s_nop 0
	global_load_lds_dwordx4 v136, s[30:31] sc1
	s_mov_b32 m0, s40
	s_nop 0
	global_load_lds_dwordx4 v132, s[56:57] sc1
	s_mov_b32 m0, s41
	s_nop 0
	global_load_lds_dwordx4 v130, s[56:57] sc1
	s_waitcnt vmcnt(12)
	s_waitcnt lgkmcnt(0)
	s_setprio 1
	s_barrier
	v_mfma_f32_16x16x32_bf16 v[58:61], v[156:159], v[200:203], v[58:61]
	v_mfma_f32_16x16x32_bf16 v[46:49], v[166:169], v[200:203], v[46:49]
	v_mfma_f32_16x16x32_bf16 v[38:41], v[156:159], v[208:211], v[38:41]
	v_mfma_f32_16x16x32_bf16 v[30:33], v[166:169], v[208:211], v[30:33]
	v_mfma_f32_16x16x32_bf16 v[22:25], v[156:159], v[216:219], v[22:25]
	v_mfma_f32_16x16x32_bf16 v[14:17], v[166:169], v[216:219], v[14:17]
	v_mfma_f32_16x16x32_bf16 v[6:9], v[156:159], v[224:227], v[6:9]
	v_mfma_f32_16x16x32_bf16 v[2:5], v[166:169], v[224:227], v[2:5]
	v_mfma_f32_16x16x32_bf16 v[58:61], v[162:165], v[204:207], v[58:61]
	v_mfma_f32_16x16x32_bf16 v[46:49], v[170:173], v[204:207], v[46:49]
	v_mfma_f32_16x16x32_bf16 v[38:41], v[162:165], v[212:215], v[38:41]
	v_mfma_f32_16x16x32_bf16 v[30:33], v[170:173], v[212:215], v[30:33]
	v_mfma_f32_16x16x32_bf16 v[22:25], v[162:165], v[220:223], v[22:25]
	v_mfma_f32_16x16x32_bf16 v[14:17], v[170:173], v[220:223], v[14:17]
	v_mfma_f32_16x16x32_bf16 v[6:9], v[162:165], v[228:231], v[6:9]
	v_mfma_f32_16x16x32_bf16 v[2:5], v[170:173], v[228:231], v[2:5]
	v_mfma_f32_16x16x32_bf16 v[74:77], v[174:177], v[200:203], v[74:77]
	v_mfma_f32_16x16x32_bf16 v[66:69], v[182:185], v[200:203], v[66:69]
	v_mfma_f32_16x16x32_bf16 v[50:53], v[174:177], v[208:211], v[50:53]
	v_mfma_f32_16x16x32_bf16 v[42:45], v[182:185], v[208:211], v[42:45]
	v_mfma_f32_16x16x32_bf16 v[34:37], v[174:177], v[216:219], v[34:37]
	v_mfma_f32_16x16x32_bf16 v[26:29], v[182:185], v[216:219], v[26:29]
	v_mfma_f32_16x16x32_bf16 v[18:21], v[174:177], v[224:227], v[18:21]
	v_mfma_f32_16x16x32_bf16 v[10:13], v[182:185], v[224:227], v[10:13]
	v_mfma_f32_16x16x32_bf16 v[74:77], v[178:181], v[204:207], v[74:77]
	v_mfma_f32_16x16x32_bf16 v[66:69], v[192:195], v[204:207], v[66:69]
	v_mfma_f32_16x16x32_bf16 v[50:53], v[178:181], v[212:215], v[50:53]
	v_mfma_f32_16x16x32_bf16 v[42:45], v[192:195], v[212:215], v[42:45]
	v_mfma_f32_16x16x32_bf16 v[34:37], v[178:181], v[220:223], v[34:37]
	v_mfma_f32_16x16x32_bf16 v[26:29], v[192:195], v[220:223], v[26:29]
	s_setprio 2
	s_barrier
	v_mfma_f32_16x16x32_bf16 v[18:21], v[178:181], v[228:231], v[18:21]
	v_mfma_f32_16x16x32_bf16 v[10:13], v[192:195], v[228:231], v[10:13]
	s_setprio 0
	s_add_i32 s67, s67, 2
	s_add_u32 s61, s61, 0x10000
	s_addc_u32 s66, s66, 0
	s_cmp_gt_u32 s67, 13
	s_mov_b64 s[30:31], s[52:53]
	s_branch .LBB0_268

.LBB0_1093:
	v_add_u32_e32 v155, s47, v148
	ds_read_b128 v[156:159], v155
	ds_read_b128 v[160:163], v155 offset:1024
	ds_read_b128 v[164:167], v155 offset:2048
	ds_read_b128 v[168:171], v155 offset:3072
	v_add_u32_e32 v155, s48, v148
	ds_read_b128 v[172:175], v155
	ds_read_b128 v[176:179], v155 offset:1024
	ds_read_b128 v[180:183], v155 offset:2048
	ds_read_b128 v[184:187], v155 offset:3072
	s_add_u32 s40, s18, 0x10000
	s_addc_u32 s41, s19, 0
	s_cmp_eq_u32 s78, 12
	s_cselect_b32 s64, s69, s40
	s_cselect_b32 s65, s55, s41
	s_cselect_b32 s62, s71, s76
	s_cselect_b32 s63, s70, s77
	s_add_u32 s56, s64, 0x8000
	s_addc_u32 s57, s65, 0
	s_add_i32 m0, s37, 0xc000
	ds_read_b128 v[192:195], v154
	ds_read_b128 v[200:203], v154 offset:1024
	ds_read_b128 v[204:207], v154 offset:2048
	ds_read_b128 v[208:211], v154 offset:3072
	ds_read_b128 v[212:215], v154 offset:4096
	ds_read_b128 v[216:219], v154 offset:5120
	ds_read_b128 v[220:223], v154 offset:6144
	ds_read_b128 v[224:227], v154 offset:7168
	global_load_lds_dwordx4 v144, s[18:19] sc1
	s_add_i32 m0, s37, 0xe000
	s_nop 0
	global_load_lds_dwordx4 v146, s[18:19] sc1
	s_waitcnt vmcnt(8)
	s_waitcnt lgkmcnt(0)
	s_setprio 1
	s_barrier
	v_mfma_f32_16x16x32_bf16 v[116:119], v[156:159], v[192:195], v[116:119]
	v_mfma_f32_16x16x32_bf16 v[108:111], v[164:167], v[192:195], v[108:111]
	v_mfma_f32_16x16x32_bf16 v[100:103], v[156:159], v[204:207], v[100:103]
	v_mfma_f32_16x16x32_bf16 v[92:95], v[164:167], v[204:207], v[92:95]
	v_mfma_f32_16x16x32_bf16 v[84:87], v[156:159], v[212:215], v[84:87]
	v_mfma_f32_16x16x32_bf16 v[76:79], v[164:167], v[212:215], v[76:79]
	v_mfma_f32_16x16x32_bf16 v[60:63], v[156:159], v[220:223], v[60:63]
	v_mfma_f32_16x16x32_bf16 v[52:55], v[164:167], v[220:223], v[52:55]
	v_mfma_f32_16x16x32_bf16 v[116:119], v[160:163], v[200:203], v[116:119]
	v_mfma_f32_16x16x32_bf16 v[108:111], v[168:171], v[200:203], v[108:111]
	v_mfma_f32_16x16x32_bf16 v[100:103], v[160:163], v[208:211], v[100:103]
	v_mfma_f32_16x16x32_bf16 v[92:95], v[168:171], v[208:211], v[92:95]
	v_mfma_f32_16x16x32_bf16 v[84:87], v[160:163], v[216:219], v[84:87]
	v_mfma_f32_16x16x32_bf16 v[76:79], v[168:171], v[216:219], v[76:79]
	v_mfma_f32_16x16x32_bf16 v[60:63], v[160:163], v[224:227], v[60:63]
	v_mfma_f32_16x16x32_bf16 v[52:55], v[168:171], v[224:227], v[52:55]
	v_mfma_f32_16x16x32_bf16 v[124:127], v[172:175], v[192:195], v[124:127]
	v_mfma_f32_16x16x32_bf16 v[120:123], v[180:183], v[192:195], v[120:123]
	v_mfma_f32_16x16x32_bf16 v[112:115], v[172:175], v[204:207], v[112:115]
	v_mfma_f32_16x16x32_bf16 v[104:107], v[180:183], v[204:207], v[104:107]
	v_mfma_f32_16x16x32_bf16 v[96:99], v[172:175], v[212:215], v[96:99]
	v_mfma_f32_16x16x32_bf16 v[88:91], v[180:183], v[212:215], v[88:91]
	v_mfma_f32_16x16x32_bf16 v[80:83], v[172:175], v[220:223], v[80:83]
	v_mfma_f32_16x16x32_bf16 v[68:71], v[180:183], v[220:223], v[68:71]
	v_mfma_f32_16x16x32_bf16 v[124:127], v[176:179], v[200:203], v[124:127]
	v_mfma_f32_16x16x32_bf16 v[120:123], v[184:187], v[200:203], v[120:123]
	v_mfma_f32_16x16x32_bf16 v[112:115], v[176:179], v[208:211], v[112:115]
	v_mfma_f32_16x16x32_bf16 v[104:107], v[184:187], v[208:211], v[104:107]
	v_mfma_f32_16x16x32_bf16 v[96:99], v[176:179], v[216:219], v[96:99]
	v_mfma_f32_16x16x32_bf16 v[88:91], v[184:187], v[216:219], v[88:91]
	s_setprio 2
	s_barrier
	v_mfma_f32_16x16x32_bf16 v[80:83], v[176:179], v[224:227], v[80:83]
	v_mfma_f32_16x16x32_bf16 v[68:71], v[184:187], v[224:227], v[68:71]
	s_setprio 0
	s_add_i32 s18, s47, s36
	s_mov_b32 m0, s18
	ds_read_b128 v[192:195], v154 offset:16384
	ds_read_b128 v[200:203], v154 offset:17408
	ds_read_b128 v[204:207], v154 offset:18432
	ds_read_b128 v[208:211], v154 offset:19456
	ds_read_b128 v[212:215], v154 offset:20480
	ds_read_b128 v[216:219], v154 offset:21504
	ds_read_b128 v[220:223], v154 offset:22528
	ds_read_b128 v[224:227], v154 offset:23552
	global_load_lds_dwordx4 v132, s[62:63] sc1
	s_add_i32 m0, s18, 0x2000
	s_add_u32 s18, s62, 0x4000
	s_addc_u32 s19, s63, 0
	s_add_i32 s79, s48, s36
	global_load_lds_dwordx4 v134, s[62:63] sc1
	s_mov_b32 m0, s79
	s_nop 0
	global_load_lds_dwordx4 v132, s[18:19] sc1
	s_add_i32 m0, s79, 0x2000
	s_nop 0
	global_load_lds_dwordx4 v134, s[18:19] sc1
	s_mov_b32 m0, s37
	s_nop 0
	global_load_lds_dwordx4 v130, s[64:65] sc1
	s_mov_b32 m0, s42
	s_nop 0
	global_load_lds_dwordx4 v128, s[64:65] sc1
	s_waitcnt vmcnt(8)
	s_waitcnt lgkmcnt(0)
	s_setprio 1
	s_barrier
	v_mfma_f32_16x16x32_bf16 v[56:59], v[156:159], v[192:195], v[56:59]
	v_mfma_f32_16x16x32_bf16 v[44:47], v[164:167], v[192:195], v[44:47]
	v_mfma_f32_16x16x32_bf16 v[36:39], v[156:159], v[204:207], v[36:39]
	v_mfma_f32_16x16x32_bf16 v[28:31], v[164:167], v[204:207], v[28:31]
	v_mfma_f32_16x16x32_bf16 v[20:23], v[156:159], v[212:215], v[20:23]
	v_mfma_f32_16x16x32_bf16 v[12:15], v[164:167], v[212:215], v[12:15]
	v_mfma_f32_16x16x32_bf16 v[4:7], v[156:159], v[220:223], v[4:7]
	v_mfma_f32_16x16x32_bf16 v[0:3], v[164:167], v[220:223], v[0:3]
	v_mfma_f32_16x16x32_bf16 v[56:59], v[160:163], v[200:203], v[56:59]
	v_mfma_f32_16x16x32_bf16 v[44:47], v[168:171], v[200:203], v[44:47]
	v_mfma_f32_16x16x32_bf16 v[36:39], v[160:163], v[208:211], v[36:39]
	v_mfma_f32_16x16x32_bf16 v[28:31], v[168:171], v[208:211], v[28:31]
	v_mfma_f32_16x16x32_bf16 v[20:23], v[160:163], v[216:219], v[20:23]
	v_mfma_f32_16x16x32_bf16 v[12:15], v[168:171], v[216:219], v[12:15]
	v_mfma_f32_16x16x32_bf16 v[4:7], v[160:163], v[224:227], v[4:7]
	v_mfma_f32_16x16x32_bf16 v[0:3], v[168:171], v[224:227], v[0:3]
	v_mfma_f32_16x16x32_bf16 v[72:75], v[172:175], v[192:195], v[72:75]
	v_mfma_f32_16x16x32_bf16 v[64:67], v[180:183], v[192:195], v[64:67]
	v_mfma_f32_16x16x32_bf16 v[48:51], v[172:175], v[204:207], v[48:51]
	v_mfma_f32_16x16x32_bf16 v[40:43], v[180:183], v[204:207], v[40:43]
	v_mfma_f32_16x16x32_bf16 v[32:35], v[172:175], v[212:215], v[32:35]
	v_mfma_f32_16x16x32_bf16 v[24:27], v[180:183], v[212:215], v[24:27]
	v_mfma_f32_16x16x32_bf16 v[16:19], v[172:175], v[220:223], v[16:19]
	v_mfma_f32_16x16x32_bf16 v[8:11], v[180:183], v[220:223], v[8:11]
	v_mfma_f32_16x16x32_bf16 v[72:75], v[176:179], v[200:203], v[72:75]
	v_mfma_f32_16x16x32_bf16 v[64:67], v[184:187], v[200:203], v[64:67]
	v_mfma_f32_16x16x32_bf16 v[48:51], v[176:179], v[208:211], v[48:51]
	v_mfma_f32_16x16x32_bf16 v[40:43], v[184:187], v[208:211], v[40:43]
	v_mfma_f32_16x16x32_bf16 v[32:35], v[176:179], v[216:219], v[32:35]
	v_mfma_f32_16x16x32_bf16 v[24:27], v[184:187], v[216:219], v[24:27]
	s_setprio 2
	s_barrier
	v_mfma_f32_16x16x32_bf16 v[16:19], v[176:179], v[224:227], v[16:19]
	v_mfma_f32_16x16x32_bf16 v[8:11], v[184:187], v[224:227], v[8:11]
	s_setprio 0
	v_add_u32_e32 v155, s49, v148
	ds_read_b128 v[156:159], v155
	ds_read_b128 v[160:163], v155 offset:1024
	ds_read_b128 v[164:167], v155 offset:2048
	ds_read_b128 v[168:171], v155 offset:3072
	v_add_u32_e32 v155, s50, v148
	ds_read_b128 v[172:175], v155
	ds_read_b128 v[176:179], v155 offset:1024
	ds_read_b128 v[180:183], v155 offset:2048
	ds_read_b128 v[184:187], v155 offset:3072
	s_add_u32 s18, s64, 0x4000
	s_addc_u32 s19, s65, 0
	s_mov_b32 m0, s43
	ds_read_b128 v[192:195], v154 offset:32768
	ds_read_b128 v[200:203], v154 offset:33792
	ds_read_b128 v[204:207], v154 offset:34816
	ds_read_b128 v[208:211], v154 offset:35840
	ds_read_b128 v[212:215], v154 offset:36864
	ds_read_b128 v[216:219], v154 offset:37888
	ds_read_b128 v[220:223], v154 offset:38912
	ds_read_b128 v[224:227], v154 offset:39936
	global_load_lds_dwordx4 v130, s[18:19] sc1
	s_mov_b32 m0, s44
	s_nop 0
	global_load_lds_dwordx4 v128, s[18:19] sc1
	s_waitcnt vmcnt(8)
	s_waitcnt lgkmcnt(0)
	s_setprio 1
	s_barrier
	v_mfma_f32_16x16x32_bf16 v[116:119], v[156:159], v[192:195], v[116:119]
	v_mfma_f32_16x16x32_bf16 v[108:111], v[164:167], v[192:195], v[108:111]
	v_mfma_f32_16x16x32_bf16 v[100:103], v[156:159], v[204:207], v[100:103]
	v_mfma_f32_16x16x32_bf16 v[92:95], v[164:167], v[204:207], v[92:95]
	v_mfma_f32_16x16x32_bf16 v[84:87], v[156:159], v[212:215], v[84:87]
	v_mfma_f32_16x16x32_bf16 v[76:79], v[164:167], v[212:215], v[76:79]
	v_mfma_f32_16x16x32_bf16 v[60:63], v[156:159], v[220:223], v[60:63]
	v_mfma_f32_16x16x32_bf16 v[52:55], v[164:167], v[220:223], v[52:55]
	v_mfma_f32_16x16x32_bf16 v[116:119], v[160:163], v[200:203], v[116:119]
	v_mfma_f32_16x16x32_bf16 v[108:111], v[168:171], v[200:203], v[108:111]
	v_mfma_f32_16x16x32_bf16 v[100:103], v[160:163], v[208:211], v[100:103]
	v_mfma_f32_16x16x32_bf16 v[92:95], v[168:171], v[208:211], v[92:95]
	v_mfma_f32_16x16x32_bf16 v[84:87], v[160:163], v[216:219], v[84:87]
	v_mfma_f32_16x16x32_bf16 v[76:79], v[168:171], v[216:219], v[76:79]
	v_mfma_f32_16x16x32_bf16 v[60:63], v[160:163], v[224:227], v[60:63]
	v_mfma_f32_16x16x32_bf16 v[52:55], v[168:171], v[224:227], v[52:55]
	v_mfma_f32_16x16x32_bf16 v[124:127], v[172:175], v[192:195], v[124:127]
	v_mfma_f32_16x16x32_bf16 v[120:123], v[180:183], v[192:195], v[120:123]
	v_mfma_f32_16x16x32_bf16 v[112:115], v[172:175], v[204:207], v[112:115]
	v_mfma_f32_16x16x32_bf16 v[104:107], v[180:183], v[204:207], v[104:107]
	v_mfma_f32_16x16x32_bf16 v[96:99], v[172:175], v[212:215], v[96:99]
	v_mfma_f32_16x16x32_bf16 v[88:91], v[180:183], v[212:215], v[88:91]
	v_mfma_f32_16x16x32_bf16 v[80:83], v[172:175], v[220:223], v[80:83]
	v_mfma_f32_16x16x32_bf16 v[68:71], v[180:183], v[220:223], v[68:71]
	v_mfma_f32_16x16x32_bf16 v[124:127], v[176:179], v[200:203], v[124:127]
	v_mfma_f32_16x16x32_bf16 v[120:123], v[184:187], v[200:203], v[120:123]
	v_mfma_f32_16x16x32_bf16 v[112:115], v[176:179], v[208:211], v[112:115]
	v_mfma_f32_16x16x32_bf16 v[104:107], v[184:187], v[208:211], v[104:107]
	v_mfma_f32_16x16x32_bf16 v[96:99], v[176:179], v[216:219], v[96:99]
	v_mfma_f32_16x16x32_bf16 v[88:91], v[184:187], v[216:219], v[88:91]
	s_setprio 2
	s_barrier
	v_mfma_f32_16x16x32_bf16 v[80:83], v[176:179], v[224:227], v[80:83]
	v_mfma_f32_16x16x32_bf16 v[68:71], v[184:187], v[224:227], v[68:71]
	s_setprio 0
	s_add_u32 s18, s62, 0x8000
	s_addc_u32 s19, s63, 0
	s_add_i32 s64, s49, s36
	s_mov_b32 m0, s64
	ds_read_b128 v[192:195], v154 offset:49152
	ds_read_b128 v[200:203], v154 offset:50176
	ds_read_b128 v[204:207], v154 offset:51200
	ds_read_b128 v[208:211], v154 offset:52224
	ds_read_b128 v[212:215], v154 offset:53248
	ds_read_b128 v[216:219], v154 offset:54272
	ds_read_b128 v[220:223], v154 offset:55296
	ds_read_b128 v[224:227], v154 offset:56320
	global_load_lds_dwordx4 v132, s[18:19] sc1
	s_add_i32 m0, s64, 0x2000
	s_nop 0
	global_load_lds_dwordx4 v134, s[18:19] sc1
	s_add_u32 s18, s62, 0xc000
	s_addc_u32 s19, s63, 0
	s_add_i32 s62, s50, s36
	s_mov_b32 m0, s62
	s_nop 0
	global_load_lds_dwordx4 v132, s[18:19] sc1
	s_add_i32 m0, s62, 0x2000
	s_nop 0
	global_load_lds_dwordx4 v134, s[18:19] sc1
	s_mov_b32 m0, s7
	s_nop 0
	global_load_lds_dwordx4 v130, s[56:57] sc1
	s_mov_b32 m0, s45
	s_nop 0
	global_load_lds_dwordx4 v128, s[56:57] sc1
	s_waitcnt vmcnt(8)
	s_waitcnt lgkmcnt(0)
	s_setprio 1
	s_barrier
	v_mfma_f32_16x16x32_bf16 v[56:59], v[156:159], v[192:195], v[56:59]
	v_mfma_f32_16x16x32_bf16 v[44:47], v[164:167], v[192:195], v[44:47]
	v_mfma_f32_16x16x32_bf16 v[36:39], v[156:159], v[204:207], v[36:39]
	v_mfma_f32_16x16x32_bf16 v[28:31], v[164:167], v[204:207], v[28:31]
	v_mfma_f32_16x16x32_bf16 v[20:23], v[156:159], v[212:215], v[20:23]
	v_mfma_f32_16x16x32_bf16 v[12:15], v[164:167], v[212:215], v[12:15]
	v_mfma_f32_16x16x32_bf16 v[4:7], v[156:159], v[220:223], v[4:7]
	v_mfma_f32_16x16x32_bf16 v[0:3], v[164:167], v[220:223], v[0:3]
	v_mfma_f32_16x16x32_bf16 v[56:59], v[160:163], v[200:203], v[56:59]
	v_mfma_f32_16x16x32_bf16 v[44:47], v[168:171], v[200:203], v[44:47]
	v_mfma_f32_16x16x32_bf16 v[36:39], v[160:163], v[208:211], v[36:39]
	v_mfma_f32_16x16x32_bf16 v[28:31], v[168:171], v[208:211], v[28:31]
	v_mfma_f32_16x16x32_bf16 v[20:23], v[160:163], v[216:219], v[20:23]
	v_mfma_f32_16x16x32_bf16 v[12:15], v[168:171], v[216:219], v[12:15]
	v_mfma_f32_16x16x32_bf16 v[4:7], v[160:163], v[224:227], v[4:7]
	v_mfma_f32_16x16x32_bf16 v[0:3], v[168:171], v[224:227], v[0:3]
	v_mfma_f32_16x16x32_bf16 v[72:75], v[172:175], v[192:195], v[72:75]
	v_mfma_f32_16x16x32_bf16 v[64:67], v[180:183], v[192:195], v[64:67]
	v_mfma_f32_16x16x32_bf16 v[48:51], v[172:175], v[204:207], v[48:51]
	v_mfma_f32_16x16x32_bf16 v[40:43], v[180:183], v[204:207], v[40:43]
	v_mfma_f32_16x16x32_bf16 v[32:35], v[172:175], v[212:215], v[32:35]
	v_mfma_f32_16x16x32_bf16 v[24:27], v[180:183], v[212:215], v[24:27]
	v_mfma_f32_16x16x32_bf16 v[16:19], v[172:175], v[220:223], v[16:19]
	v_mfma_f32_16x16x32_bf16 v[8:11], v[180:183], v[220:223], v[8:11]
	v_mfma_f32_16x16x32_bf16 v[72:75], v[176:179], v[200:203], v[72:75]
	v_mfma_f32_16x16x32_bf16 v[64:67], v[184:187], v[200:203], v[64:67]
	v_mfma_f32_16x16x32_bf16 v[48:51], v[176:179], v[208:211], v[48:51]
	v_mfma_f32_16x16x32_bf16 v[40:43], v[184:187], v[208:211], v[40:43]
	v_mfma_f32_16x16x32_bf16 v[32:35], v[176:179], v[216:219], v[32:35]
	v_mfma_f32_16x16x32_bf16 v[24:27], v[184:187], v[216:219], v[24:27]
	s_setprio 2
	s_barrier
	v_mfma_f32_16x16x32_bf16 v[16:19], v[176:179], v[224:227], v[16:19]
	v_mfma_f32_16x16x32_bf16 v[8:11], v[184:187], v[224:227], v[8:11]
	s_setprio 0
	s_add_i32 s78, s78, 2
	s_add_u32 s76, s76, 0x10000
	s_addc_u32 s77, s77, 0
	s_cmp_gt_u32 s78, 13
	s_mov_b64 s[18:19], s[40:41]
	s_cbranch_scc0 .LBB0_1093
	s_cmp_eq_u32 s54, s59
	s_cbranch_scc1 .Lemb7_last
	s_mov_b32 s98, s54
	s_mov_b32 s54, s35
	s_add_i32 s35, s35, 1
	s_cmp_lt_u32 s35, s12
	s_mov_b64 s[40:41], s[16:17]
	s_mov_b32 s16, s61
	s_cselect_b64 s[56:57], -1, 0
	s_add_i32 s61, s35, s6
	s_mov_b64 s[18:19], s[0:1]
	s_and_b64 s[0:1], s[56:57], exec
	s_cselect_b32 s0, s58, s58
	s_cselect_b32 s16, s61, s16
	s_ashr_i32 s1, s0, 31
	s_lshl_b64 s[0:1], s[0:1], 19
	s_add_u32 s0, s60, s0
	s_addc_u32 s1, s33, s1
	s_and_b64 s[62:63], s[56:57], exec
	s_cselect_b32 s55, s1, s19
	s_cselect_b32 s69, s0, s18
	s_ashr_i32 s17, s16, 31
	s_lshl_b64 s[16:17], s[16:17], 19
	s_add_u32 s16, s66, s16
	s_addc_u32 s17, s67, s17
	s_and_b64 s[56:57], s[56:57], exec
	s_cselect_b32 s70, s17, s41
	s_cselect_b32 s71, s16, s40
	s_add_u32 s76, s40, 0x10000
	s_addc_u32 s77, s41, 0
	s_mov_b32 s78, -2
	v_add_u32_e32 v155, s47, v148
	ds_read_b128 v[156:159], v155
	ds_read_b128 v[160:163], v155 offset:1024
	ds_read_b128 v[164:167], v155 offset:2048
	ds_read_b128 v[168:171], v155 offset:3072
	v_add_u32_e32 v155, s48, v148
	ds_read_b128 v[172:175], v155
	ds_read_b128 v[176:179], v155 offset:1024
	ds_read_b128 v[180:183], v155 offset:2048
	ds_read_b128 v[184:187], v155 offset:3072
	s_add_u32 s40, s18, 0x10000
	s_addc_u32 s41, s19, 0
	s_cmp_eq_u32 s78, 12
	s_cselect_b32 s64, s69, s40
	s_cselect_b32 s65, s55, s41
	s_cselect_b32 s62, s71, s76
	s_cselect_b32 s63, s70, s77
	s_add_u32 s56, s64, 0x8000
	s_addc_u32 s57, s65, 0
	s_add_i32 m0, s37, 0xc000
	ds_read_b128 v[192:195], v154
	ds_read_b128 v[200:203], v154 offset:1024
	ds_read_b128 v[204:207], v154 offset:2048
	ds_read_b128 v[208:211], v154 offset:3072
	ds_read_b128 v[212:215], v154 offset:4096
	ds_read_b128 v[216:219], v154 offset:5120
	ds_read_b128 v[220:223], v154 offset:6144
	ds_read_b128 v[224:227], v154 offset:7168
	v_lshl_add_u32 v133, s98, 10, v153
	ds_read_b32 v228, v133
	ds_read_b32 v229, v133 offset:64
	ds_read_b32 v230, v133 offset:128
	ds_read_b32 v231, v133 offset:192
	global_load_lds_dwordx4 v144, s[18:19] sc1
	s_add_i32 m0, s37, 0xe000
	s_nop 0
	global_load_lds_dwordx4 v146, s[18:19] sc1
	s_waitcnt vmcnt(8)
	s_waitcnt lgkmcnt(0)
	s_setprio 1
	s_barrier
	s_add_i32 s99, s98, s6
	s_lshl_b32 s99, s99, 15
	s_or_b32 s99, s99, s51
	s_and_b32 s99, s99, 0xffffc000
	s_add_i32 s100, s99, s46
	v_mul_f32_e32 v248, 0xbfb8aa3b, v228
	v_mul_f32_e32 v249, v228, v228
	v_rcp_f32_e32 v250, v249
	v_mul_f32_e32 v232, v116, v248
	v_mul_f32_e32 v233, v117, v248
	v_mul_f32_e32 v234, v118, v248
	v_mul_f32_e32 v235, v119, v248
	v_mul_f32_e32 v236, v108, v248
	v_mul_f32_e32 v237, v109, v248
	v_mul_f32_e32 v238, v110, v248
	v_mul_f32_e32 v239, v111, v248
	v_mul_f32_e32 v240, v116, v124
	v_mul_f32_e32 v241, v117, v125
	v_mul_f32_e32 v242, v118, v126
	v_mul_f32_e32 v243, v119, v127
	v_mul_f32_e32 v244, v108, v120
	v_mul_f32_e32 v245, v109, v121
	v_mul_f32_e32 v246, v110, v122
	v_mul_f32_e32 v247, v111, v123
	v_exp_f32_e32 v232, v232
	v_exp_f32_e32 v233, v233
	v_exp_f32_e32 v234, v234
	v_exp_f32_e32 v235, v235
	v_mfma_f32_16x16x32_bf16 v[116:119], v[156:159], v[192:195], 0
	v_exp_f32_e32 v236, v236
	v_exp_f32_e32 v237, v237
	v_exp_f32_e32 v238, v238
	v_exp_f32_e32 v239, v239
	v_mfma_f32_16x16x32_bf16 v[108:111], v[164:167], v[192:195], 0
	v_fma_f32 v232, v232, v250, v250
	v_fma_f32 v233, v233, v250, v250
	v_fma_f32 v234, v234, v250, v250
	v_fma_f32 v235, v235, v250, v250
	v_mfma_f32_16x16x32_bf16 v[124:127], v[172:175], v[192:195], 0
	v_fma_f32 v236, v236, v250, v250
	v_fma_f32 v237, v237, v250, v250
	v_fma_f32 v238, v238, v250, v250
	v_fma_f32 v239, v239, v250, v250
	v_mfma_f32_16x16x32_bf16 v[120:123], v[180:183], v[192:195], 0
	v_rcp_f32_e32 v232, v232
	v_rcp_f32_e32 v233, v233
	v_rcp_f32_e32 v234, v234
	v_rcp_f32_e32 v235, v235
	v_mfma_f32_16x16x32_bf16 v[116:119], v[160:163], v[200:203], v[116:119]
	v_rcp_f32_e32 v236, v236
	v_rcp_f32_e32 v237, v237
	v_rcp_f32_e32 v238, v238
	v_rcp_f32_e32 v239, v239
	v_mfma_f32_16x16x32_bf16 v[108:111], v[168:171], v[200:203], v[108:111]
	v_or_b32_e32 v251, s100, v137
	v_lshlrev_b32_e32 v251, 1, v251
	v_mul_f32_e32 v240, v240, v232
	v_mul_f32_e32 v241, v241, v233
	v_mfma_f32_16x16x32_bf16 v[124:127], v[176:179], v[200:203], v[124:127]
	v_mul_f32_e32 v242, v242, v234
	v_mul_f32_e32 v243, v243, v235
	v_mul_f32_e32 v244, v244, v236
	v_mul_f32_e32 v245, v245, v237
	v_mfma_f32_16x16x32_bf16 v[120:123], v[184:187], v[200:203], v[120:123]
	v_mul_f32_e32 v246, v246, v238
	v_mul_f32_e32 v247, v247, v239
	v_cvt_pk_bf16_f32 v232, v240, v241
	v_cvt_pk_bf16_f32 v233, v242, v243
	v_cvt_pk_bf16_f32 v234, v244, v245
	v_cvt_pk_bf16_f32 v235, v246, v247
	buffer_store_dwordx4 v[232:235], v251, s[72:75], 0 offen sc1
	v_mul_f32_e32 v248, 0xbfb8aa3b, v229
	v_mul_f32_e32 v249, v229, v229
	v_rcp_f32_e32 v250, v249
	v_mul_f32_e32 v232, v100, v248
	v_mul_f32_e32 v233, v101, v248
	v_mul_f32_e32 v234, v102, v248
	v_mul_f32_e32 v235, v103, v248
	v_mul_f32_e32 v236, v92, v248
	v_mul_f32_e32 v237, v93, v248
	v_mul_f32_e32 v238, v94, v248
	v_mul_f32_e32 v239, v95, v248
	v_mul_f32_e32 v240, v100, v112
	v_mul_f32_e32 v241, v101, v113
	v_mul_f32_e32 v242, v102, v114
	v_mul_f32_e32 v243, v103, v115
	v_mul_f32_e32 v244, v92, v104
	v_mul_f32_e32 v245, v93, v105
	v_mul_f32_e32 v246, v94, v106
	v_mul_f32_e32 v247, v95, v107
	v_exp_f32_e32 v232, v232
	v_exp_f32_e32 v233, v233
	v_exp_f32_e32 v234, v234
	v_exp_f32_e32 v235, v235
	v_mfma_f32_16x16x32_bf16 v[100:103], v[156:159], v[204:207], 0
	v_exp_f32_e32 v236, v236
	v_exp_f32_e32 v237, v237
	v_exp_f32_e32 v238, v238
	v_exp_f32_e32 v239, v239
	v_mfma_f32_16x16x32_bf16 v[92:95], v[164:167], v[204:207], 0
	v_fma_f32 v232, v232, v250, v250
	v_fma_f32 v233, v233, v250, v250
	v_fma_f32 v234, v234, v250, v250
	v_fma_f32 v235, v235, v250, v250
	v_mfma_f32_16x16x32_bf16 v[112:115], v[172:175], v[204:207], 0
	v_fma_f32 v236, v236, v250, v250
	v_fma_f32 v237, v237, v250, v250
	v_fma_f32 v238, v238, v250, v250
	v_fma_f32 v239, v239, v250, v250
	v_mfma_f32_16x16x32_bf16 v[104:107], v[180:183], v[204:207], 0
	v_rcp_f32_e32 v232, v232
	v_rcp_f32_e32 v233, v233
	v_rcp_f32_e32 v234, v234
	v_rcp_f32_e32 v235, v235
	v_mfma_f32_16x16x32_bf16 v[100:103], v[160:163], v[208:211], v[100:103]
	v_rcp_f32_e32 v236, v236
	v_rcp_f32_e32 v237, v237
	v_rcp_f32_e32 v238, v238
	v_rcp_f32_e32 v239, v239
	v_mfma_f32_16x16x32_bf16 v[92:95], v[168:171], v[208:211], v[92:95]
	v_or_b32_e32 v251, s100, v139
	v_lshlrev_b32_e32 v251, 1, v251
	v_mul_f32_e32 v240, v240, v232
	v_mul_f32_e32 v241, v241, v233
	v_mfma_f32_16x16x32_bf16 v[112:115], v[176:179], v[208:211], v[112:115]
	v_mul_f32_e32 v242, v242, v234
	v_mul_f32_e32 v243, v243, v235
	v_mul_f32_e32 v244, v244, v236
	v_mul_f32_e32 v245, v245, v237
	v_mfma_f32_16x16x32_bf16 v[104:107], v[184:187], v[208:211], v[104:107]
	v_mul_f32_e32 v246, v246, v238
	v_mul_f32_e32 v247, v247, v239
	v_cvt_pk_bf16_f32 v232, v240, v241
	v_cvt_pk_bf16_f32 v233, v242, v243
	v_cvt_pk_bf16_f32 v234, v244, v245
	v_cvt_pk_bf16_f32 v235, v246, v247
	buffer_store_dwordx4 v[232:235], v251, s[72:75], 0 offen sc1
	v_mul_f32_e32 v248, 0xbfb8aa3b, v230
	v_mul_f32_e32 v249, v230, v230
	v_rcp_f32_e32 v250, v249
	v_mul_f32_e32 v232, v84, v248
	v_mul_f32_e32 v233, v85, v248
	v_mul_f32_e32 v234, v86, v248
	v_mul_f32_e32 v235, v87, v248
	v_mul_f32_e32 v236, v76, v248
	v_mul_f32_e32 v237, v77, v248
	v_mul_f32_e32 v238, v78, v248
	v_mul_f32_e32 v239, v79, v248
	v_mul_f32_e32 v240, v84, v96
	v_mul_f32_e32 v241, v85, v97
	v_mul_f32_e32 v242, v86, v98
	v_mul_f32_e32 v243, v87, v99
	v_mul_f32_e32 v244, v76, v88
	v_mul_f32_e32 v245, v77, v89
	v_mul_f32_e32 v246, v78, v90
	v_mul_f32_e32 v247, v79, v91
	v_exp_f32_e32 v232, v232
	v_exp_f32_e32 v233, v233
	v_exp_f32_e32 v234, v234
	v_exp_f32_e32 v235, v235
	v_mfma_f32_16x16x32_bf16 v[84:87], v[156:159], v[212:215], 0
	v_exp_f32_e32 v236, v236
	v_exp_f32_e32 v237, v237
	v_exp_f32_e32 v238, v238
	v_exp_f32_e32 v239, v239
	v_mfma_f32_16x16x32_bf16 v[76:79], v[164:167], v[212:215], 0
	v_fma_f32 v232, v232, v250, v250
	v_fma_f32 v233, v233, v250, v250
	v_fma_f32 v234, v234, v250, v250
	v_fma_f32 v235, v235, v250, v250
	v_mfma_f32_16x16x32_bf16 v[96:99], v[172:175], v[212:215], 0
	v_fma_f32 v236, v236, v250, v250
	v_fma_f32 v237, v237, v250, v250
	v_fma_f32 v238, v238, v250, v250
	v_fma_f32 v239, v239, v250, v250
	v_mfma_f32_16x16x32_bf16 v[88:91], v[180:183], v[212:215], 0
	v_rcp_f32_e32 v232, v232
	v_rcp_f32_e32 v233, v233
	v_rcp_f32_e32 v234, v234
	v_rcp_f32_e32 v235, v235
	v_mfma_f32_16x16x32_bf16 v[84:87], v[160:163], v[216:219], v[84:87]
	v_rcp_f32_e32 v236, v236
	v_rcp_f32_e32 v237, v237
	v_rcp_f32_e32 v238, v238
	v_rcp_f32_e32 v239, v239
	v_mfma_f32_16x16x32_bf16 v[76:79], v[168:171], v[216:219], v[76:79]
	v_or_b32_e32 v251, s100, v141
	v_lshlrev_b32_e32 v251, 1, v251
	v_mul_f32_e32 v240, v240, v232
	v_mul_f32_e32 v241, v241, v233
	v_mfma_f32_16x16x32_bf16 v[96:99], v[176:179], v[216:219], v[96:99]
	v_mul_f32_e32 v242, v242, v234
	v_mul_f32_e32 v243, v243, v235
	v_mul_f32_e32 v244, v244, v236
	v_mul_f32_e32 v245, v245, v237
	v_mfma_f32_16x16x32_bf16 v[88:91], v[184:187], v[216:219], v[88:91]
	v_mul_f32_e32 v246, v246, v238
	v_mul_f32_e32 v247, v247, v239
	v_cvt_pk_bf16_f32 v232, v240, v241
	v_cvt_pk_bf16_f32 v233, v242, v243
	v_cvt_pk_bf16_f32 v234, v244, v245
	v_cvt_pk_bf16_f32 v235, v246, v247
	buffer_store_dwordx4 v[232:235], v251, s[72:75], 0 offen sc1
	v_mul_f32_e32 v248, 0xbfb8aa3b, v231
	v_mul_f32_e32 v249, v231, v231
	v_rcp_f32_e32 v250, v249
	v_mul_f32_e32 v232, v60, v248
	v_mul_f32_e32 v233, v61, v248
	v_mul_f32_e32 v234, v62, v248
	v_mul_f32_e32 v235, v63, v248
	v_mul_f32_e32 v236, v52, v248
	v_mul_f32_e32 v237, v53, v248
	v_mul_f32_e32 v238, v54, v248
	v_mul_f32_e32 v239, v55, v248
	v_mul_f32_e32 v240, v60, v80
	v_mul_f32_e32 v241, v61, v81
	v_mul_f32_e32 v242, v62, v82
	v_mul_f32_e32 v243, v63, v83
	v_mul_f32_e32 v244, v52, v68
	v_mul_f32_e32 v245, v53, v69
	v_mul_f32_e32 v246, v54, v70
	v_mul_f32_e32 v247, v55, v71
	v_exp_f32_e32 v232, v232
	v_exp_f32_e32 v233, v233
	v_exp_f32_e32 v234, v234
	v_exp_f32_e32 v235, v235
	v_mfma_f32_16x16x32_bf16 v[60:63], v[156:159], v[220:223], 0
	v_exp_f32_e32 v236, v236
	v_exp_f32_e32 v237, v237
	v_exp_f32_e32 v238, v238
	v_exp_f32_e32 v239, v239
	v_mfma_f32_16x16x32_bf16 v[52:55], v[164:167], v[220:223], 0
	v_fma_f32 v232, v232, v250, v250
	v_fma_f32 v233, v233, v250, v250
	v_fma_f32 v234, v234, v250, v250
	v_fma_f32 v235, v235, v250, v250
	v_mfma_f32_16x16x32_bf16 v[80:83], v[172:175], v[220:223], 0
	v_fma_f32 v236, v236, v250, v250
	v_fma_f32 v237, v237, v250, v250
	v_fma_f32 v238, v238, v250, v250
	v_fma_f32 v239, v239, v250, v250
	v_mfma_f32_16x16x32_bf16 v[68:71], v[180:183], v[220:223], 0
	v_rcp_f32_e32 v232, v232
	v_rcp_f32_e32 v233, v233
	v_rcp_f32_e32 v234, v234
	v_rcp_f32_e32 v235, v235
	v_mfma_f32_16x16x32_bf16 v[60:63], v[160:163], v[224:227], v[60:63]
	v_rcp_f32_e32 v236, v236
	v_rcp_f32_e32 v237, v237
	v_rcp_f32_e32 v238, v238
	v_rcp_f32_e32 v239, v239
	v_mfma_f32_16x16x32_bf16 v[52:55], v[168:171], v[224:227], v[52:55]
	v_or_b32_e32 v251, s100, v143
	v_lshlrev_b32_e32 v251, 1, v251
	v_mul_f32_e32 v240, v240, v232
	v_mul_f32_e32 v241, v241, v233
	v_mul_f32_e32 v242, v242, v234
	v_mul_f32_e32 v243, v243, v235
	v_mul_f32_e32 v244, v244, v236
	v_mul_f32_e32 v245, v245, v237
	v_mul_f32_e32 v246, v246, v238
	v_mul_f32_e32 v247, v247, v239
	v_cvt_pk_bf16_f32 v232, v240, v241
	v_cvt_pk_bf16_f32 v233, v242, v243
	v_cvt_pk_bf16_f32 v234, v244, v245
	v_cvt_pk_bf16_f32 v235, v246, v247
	buffer_store_dwordx4 v[232:235], v251, s[72:75], 0 offen sc1
	s_setprio 2
	s_barrier
	v_mfma_f32_16x16x32_bf16 v[80:83], v[176:179], v[224:227], v[80:83]
	v_mfma_f32_16x16x32_bf16 v[68:71], v[184:187], v[224:227], v[68:71]
	s_setprio 0
	s_add_i32 s18, s47, s36
	s_mov_b32 m0, s18
	ds_read_b128 v[192:195], v154 offset:16384
	ds_read_b128 v[200:203], v154 offset:17408
	ds_read_b128 v[204:207], v154 offset:18432
	ds_read_b128 v[208:211], v154 offset:19456
	ds_read_b128 v[212:215], v154 offset:20480
	ds_read_b128 v[216:219], v154 offset:21504
	ds_read_b128 v[220:223], v154 offset:22528
	ds_read_b128 v[224:227], v154 offset:23552
	ds_read_b32 v228, v133 offset:512
	ds_read_b32 v229, v133 offset:576
	ds_read_b32 v230, v133 offset:640
	ds_read_b32 v231, v133 offset:704
	global_load_lds_dwordx4 v132, s[62:63] sc1
	s_add_i32 m0, s18, 0x2000
	s_add_u32 s18, s62, 0x4000
	s_addc_u32 s19, s63, 0
	s_add_i32 s79, s48, s36
	global_load_lds_dwordx4 v134, s[62:63] sc1
	s_mov_b32 m0, s79
	s_nop 0
	global_load_lds_dwordx4 v132, s[18:19] sc1
	s_add_i32 m0, s79, 0x2000
	s_nop 0
	global_load_lds_dwordx4 v134, s[18:19] sc1
	s_mov_b32 m0, s37
	s_nop 0
	global_load_lds_dwordx4 v130, s[64:65] sc1
	s_mov_b32 m0, s42
	s_nop 0
	global_load_lds_dwordx4 v128, s[64:65] sc1
	s_waitcnt vmcnt(12)
	s_waitcnt lgkmcnt(0)
	s_setprio 1
	s_barrier
	v_mul_f32_e32 v248, 0xbfb8aa3b, v228
	v_mul_f32_e32 v249, v228, v228
	v_rcp_f32_e32 v250, v249
	v_mul_f32_e32 v232, v56, v248
	v_mul_f32_e32 v233, v57, v248
	v_mul_f32_e32 v234, v58, v248
	v_mul_f32_e32 v235, v59, v248
	v_mul_f32_e32 v236, v44, v248
	v_mul_f32_e32 v237, v45, v248
	v_mul_f32_e32 v238, v46, v248
	v_mul_f32_e32 v239, v47, v248
	v_mul_f32_e32 v240, v56, v72
	v_mul_f32_e32 v241, v57, v73
	v_mul_f32_e32 v242, v58, v74
	v_mul_f32_e32 v243, v59, v75
	v_mul_f32_e32 v244, v44, v64
	v_mul_f32_e32 v245, v45, v65
	v_mul_f32_e32 v246, v46, v66
	v_mul_f32_e32 v247, v47, v67
	v_exp_f32_e32 v232, v232
	v_exp_f32_e32 v233, v233
	v_exp_f32_e32 v234, v234
	v_exp_f32_e32 v235, v235
	v_mfma_f32_16x16x32_bf16 v[56:59], v[156:159], v[192:195], 0
	v_exp_f32_e32 v236, v236
	v_exp_f32_e32 v237, v237
	v_exp_f32_e32 v238, v238
	v_exp_f32_e32 v239, v239
	v_mfma_f32_16x16x32_bf16 v[44:47], v[164:167], v[192:195], 0
	v_fma_f32 v232, v232, v250, v250
	v_fma_f32 v233, v233, v250, v250
	v_fma_f32 v234, v234, v250, v250
	v_fma_f32 v235, v235, v250, v250
	v_mfma_f32_16x16x32_bf16 v[72:75], v[172:175], v[192:195], 0
	v_fma_f32 v236, v236, v250, v250
	v_fma_f32 v237, v237, v250, v250
	v_fma_f32 v238, v238, v250, v250
	v_fma_f32 v239, v239, v250, v250
	v_mfma_f32_16x16x32_bf16 v[64:67], v[180:183], v[192:195], 0
	v_rcp_f32_e32 v232, v232
	v_rcp_f32_e32 v233, v233
	v_rcp_f32_e32 v234, v234
	v_rcp_f32_e32 v235, v235
	v_mfma_f32_16x16x32_bf16 v[56:59], v[160:163], v[200:203], v[56:59]
	v_rcp_f32_e32 v236, v236
	v_rcp_f32_e32 v237, v237
	v_rcp_f32_e32 v238, v238
	v_rcp_f32_e32 v239, v239
	v_mfma_f32_16x16x32_bf16 v[44:47], v[168:171], v[200:203], v[44:47]
	v_add_u32_e32 v251, s99, v136
	v_or_b32_e32 v251, v251, v149
	v_lshlrev_b32_e32 v251, 1, v251
	v_mul_f32_e32 v240, v240, v232
	v_mfma_f32_16x16x32_bf16 v[72:75], v[176:179], v[200:203], v[72:75]
	v_mul_f32_e32 v241, v241, v233
	v_mul_f32_e32 v242, v242, v234
	v_mul_f32_e32 v243, v243, v235
	v_mul_f32_e32 v244, v244, v236
	v_mfma_f32_16x16x32_bf16 v[64:67], v[184:187], v[200:203], v[64:67]
	v_mul_f32_e32 v245, v245, v237
	v_mul_f32_e32 v246, v246, v238
	v_mul_f32_e32 v247, v247, v239
	v_cvt_pk_bf16_f32 v232, v240, v241
	v_cvt_pk_bf16_f32 v233, v242, v243
	v_cvt_pk_bf16_f32 v234, v244, v245
	v_cvt_pk_bf16_f32 v235, v246, v247
	buffer_store_dwordx4 v[232:235], v251, s[72:75], 0 offen sc1
	v_mul_f32_e32 v248, 0xbfb8aa3b, v229
	v_mul_f32_e32 v249, v229, v229
	v_rcp_f32_e32 v250, v249
	v_mul_f32_e32 v232, v36, v248
	v_mul_f32_e32 v233, v37, v248
	v_mul_f32_e32 v234, v38, v248
	v_mul_f32_e32 v235, v39, v248
	v_mul_f32_e32 v236, v28, v248
	v_mul_f32_e32 v237, v29, v248
	v_mul_f32_e32 v238, v30, v248
	v_mul_f32_e32 v239, v31, v248
	v_mul_f32_e32 v240, v36, v48
	v_mul_f32_e32 v241, v37, v49
	v_mul_f32_e32 v242, v38, v50
	v_mul_f32_e32 v243, v39, v51
	v_mul_f32_e32 v244, v28, v40
	v_mul_f32_e32 v245, v29, v41
	v_mul_f32_e32 v246, v30, v42
	v_mul_f32_e32 v247, v31, v43
	v_exp_f32_e32 v232, v232
	v_exp_f32_e32 v233, v233
	v_exp_f32_e32 v234, v234
	v_exp_f32_e32 v235, v235
	v_mfma_f32_16x16x32_bf16 v[36:39], v[156:159], v[204:207], 0
	v_exp_f32_e32 v236, v236
	v_exp_f32_e32 v237, v237
	v_exp_f32_e32 v238, v238
	v_exp_f32_e32 v239, v239
	v_mfma_f32_16x16x32_bf16 v[28:31], v[164:167], v[204:207], 0
	v_fma_f32 v232, v232, v250, v250
	v_fma_f32 v233, v233, v250, v250
	v_fma_f32 v234, v234, v250, v250
	v_fma_f32 v235, v235, v250, v250
	v_mfma_f32_16x16x32_bf16 v[48:51], v[172:175], v[204:207], 0
	v_fma_f32 v236, v236, v250, v250
	v_fma_f32 v237, v237, v250, v250
	v_fma_f32 v238, v238, v250, v250
	v_fma_f32 v239, v239, v250, v250
	v_mfma_f32_16x16x32_bf16 v[40:43], v[180:183], v[204:207], 0
	v_rcp_f32_e32 v232, v232
	v_rcp_f32_e32 v233, v233
	v_rcp_f32_e32 v234, v234
	v_rcp_f32_e32 v235, v235
	v_mfma_f32_16x16x32_bf16 v[36:39], v[160:163], v[208:211], v[36:39]
	v_rcp_f32_e32 v236, v236
	v_rcp_f32_e32 v237, v237
	v_rcp_f32_e32 v238, v238
	v_rcp_f32_e32 v239, v239
	v_mfma_f32_16x16x32_bf16 v[28:31], v[168:171], v[208:211], v[28:31]
	v_add_u32_e32 v251, s99, v138
	v_or_b32_e32 v251, v251, v150
	v_lshlrev_b32_e32 v251, 1, v251
	v_mul_f32_e32 v240, v240, v232
	v_mfma_f32_16x16x32_bf16 v[48:51], v[176:179], v[208:211], v[48:51]
	v_mul_f32_e32 v241, v241, v233
	v_mul_f32_e32 v242, v242, v234
	v_mul_f32_e32 v243, v243, v235
	v_mul_f32_e32 v244, v244, v236
	v_mfma_f32_16x16x32_bf16 v[40:43], v[184:187], v[208:211], v[40:43]
	v_mul_f32_e32 v245, v245, v237
	v_mul_f32_e32 v246, v246, v238
	v_mul_f32_e32 v247, v247, v239
	v_cvt_pk_bf16_f32 v232, v240, v241
	v_cvt_pk_bf16_f32 v233, v242, v243
	v_cvt_pk_bf16_f32 v234, v244, v245
	v_cvt_pk_bf16_f32 v235, v246, v247
	buffer_store_dwordx4 v[232:235], v251, s[72:75], 0 offen sc1
	v_mul_f32_e32 v248, 0xbfb8aa3b, v230
	v_mul_f32_e32 v249, v230, v230
	v_rcp_f32_e32 v250, v249
	v_mul_f32_e32 v232, v20, v248
	v_mul_f32_e32 v233, v21, v248
	v_mul_f32_e32 v234, v22, v248
	v_mul_f32_e32 v235, v23, v248
	v_mul_f32_e32 v236, v12, v248
	v_mul_f32_e32 v237, v13, v248
	v_mul_f32_e32 v238, v14, v248
	v_mul_f32_e32 v239, v15, v248
	v_mul_f32_e32 v240, v20, v32
	v_mul_f32_e32 v241, v21, v33
	v_mul_f32_e32 v242, v22, v34
	v_mul_f32_e32 v243, v23, v35
	v_mul_f32_e32 v244, v12, v24
	v_mul_f32_e32 v245, v13, v25
	v_mul_f32_e32 v246, v14, v26
	v_mul_f32_e32 v247, v15, v27
	v_exp_f32_e32 v232, v232
	v_exp_f32_e32 v233, v233
	v_exp_f32_e32 v234, v234
	v_exp_f32_e32 v235, v235
	v_mfma_f32_16x16x32_bf16 v[20:23], v[156:159], v[212:215], 0
	v_exp_f32_e32 v236, v236
	v_exp_f32_e32 v237, v237
	v_exp_f32_e32 v238, v238
	v_exp_f32_e32 v239, v239
	v_mfma_f32_16x16x32_bf16 v[12:15], v[164:167], v[212:215], 0
	v_fma_f32 v232, v232, v250, v250
	v_fma_f32 v233, v233, v250, v250
	v_fma_f32 v234, v234, v250, v250
	v_fma_f32 v235, v235, v250, v250
	v_mfma_f32_16x16x32_bf16 v[32:35], v[172:175], v[212:215], 0
	v_fma_f32 v236, v236, v250, v250
	v_fma_f32 v237, v237, v250, v250
	v_fma_f32 v238, v238, v250, v250
	v_fma_f32 v239, v239, v250, v250
	v_mfma_f32_16x16x32_bf16 v[24:27], v[180:183], v[212:215], 0
	v_rcp_f32_e32 v232, v232
	v_rcp_f32_e32 v233, v233
	v_rcp_f32_e32 v234, v234
	v_rcp_f32_e32 v235, v235
	v_mfma_f32_16x16x32_bf16 v[20:23], v[160:163], v[216:219], v[20:23]
	v_rcp_f32_e32 v236, v236
	v_rcp_f32_e32 v237, v237
	v_rcp_f32_e32 v238, v238
	v_rcp_f32_e32 v239, v239
	v_mfma_f32_16x16x32_bf16 v[12:15], v[168:171], v[216:219], v[12:15]
	v_add_u32_e32 v251, s99, v140
	v_or_b32_e32 v251, v251, v151
	v_lshlrev_b32_e32 v251, 1, v251
	v_mul_f32_e32 v240, v240, v232
	v_mfma_f32_16x16x32_bf16 v[32:35], v[176:179], v[216:219], v[32:35]
	v_mul_f32_e32 v241, v241, v233
	v_mul_f32_e32 v242, v242, v234
	v_mul_f32_e32 v243, v243, v235
	v_mul_f32_e32 v244, v244, v236
	v_mfma_f32_16x16x32_bf16 v[24:27], v[184:187], v[216:219], v[24:27]
	v_mul_f32_e32 v245, v245, v237
	v_mul_f32_e32 v246, v246, v238
	v_mul_f32_e32 v247, v247, v239
	v_cvt_pk_bf16_f32 v232, v240, v241
	v_cvt_pk_bf16_f32 v233, v242, v243
	v_cvt_pk_bf16_f32 v234, v244, v245
	v_cvt_pk_bf16_f32 v235, v246, v247
	buffer_store_dwordx4 v[232:235], v251, s[72:75], 0 offen sc1
	v_mul_f32_e32 v248, 0xbfb8aa3b, v231
	v_mul_f32_e32 v249, v231, v231
	v_rcp_f32_e32 v250, v249
	v_mul_f32_e32 v232, v4, v248
	v_mul_f32_e32 v233, v5, v248
	v_mul_f32_e32 v234, v6, v248
	v_mul_f32_e32 v235, v7, v248
	v_mul_f32_e32 v236, v0, v248
	v_mul_f32_e32 v237, v1, v248
	v_mul_f32_e32 v238, v2, v248
	v_mul_f32_e32 v239, v3, v248
	v_mul_f32_e32 v240, v4, v16
	v_mul_f32_e32 v241, v5, v17
	v_mul_f32_e32 v242, v6, v18
	v_mul_f32_e32 v243, v7, v19
	v_mul_f32_e32 v244, v0, v8
	v_mul_f32_e32 v245, v1, v9
	v_mul_f32_e32 v246, v2, v10
	v_mul_f32_e32 v247, v3, v11
	v_exp_f32_e32 v232, v232
	v_exp_f32_e32 v233, v233
	v_exp_f32_e32 v234, v234
	v_exp_f32_e32 v235, v235
	v_mfma_f32_16x16x32_bf16 v[4:7], v[156:159], v[220:223], 0
	v_exp_f32_e32 v236, v236
	v_exp_f32_e32 v237, v237
	v_exp_f32_e32 v238, v238
	v_exp_f32_e32 v239, v239
	v_mfma_f32_16x16x32_bf16 v[0:3], v[164:167], v[220:223], 0
	v_fma_f32 v232, v232, v250, v250
	v_fma_f32 v233, v233, v250, v250
	v_fma_f32 v234, v234, v250, v250
	v_fma_f32 v235, v235, v250, v250
	v_mfma_f32_16x16x32_bf16 v[16:19], v[172:175], v[220:223], 0
	v_fma_f32 v236, v236, v250, v250
	v_fma_f32 v237, v237, v250, v250
	v_fma_f32 v238, v238, v250, v250
	v_fma_f32 v239, v239, v250, v250
	v_mfma_f32_16x16x32_bf16 v[8:11], v[180:183], v[220:223], 0
	v_rcp_f32_e32 v232, v232
	v_rcp_f32_e32 v233, v233
	v_rcp_f32_e32 v234, v234
	v_rcp_f32_e32 v235, v235
	v_mfma_f32_16x16x32_bf16 v[4:7], v[160:163], v[224:227], v[4:7]
	v_rcp_f32_e32 v236, v236
	v_rcp_f32_e32 v237, v237
	v_rcp_f32_e32 v238, v238
	v_rcp_f32_e32 v239, v239
	v_mfma_f32_16x16x32_bf16 v[0:3], v[168:171], v[224:227], v[0:3]
	v_add_u32_e32 v251, s99, v142
	v_or_b32_e32 v251, v251, v152
	v_lshlrev_b32_e32 v251, 1, v251
	v_mul_f32_e32 v240, v240, v232
	v_mul_f32_e32 v241, v241, v233
	v_mul_f32_e32 v242, v242, v234
	v_mul_f32_e32 v243, v243, v235
	v_mul_f32_e32 v244, v244, v236
	v_mul_f32_e32 v245, v245, v237
	v_mul_f32_e32 v246, v246, v238
	v_mul_f32_e32 v247, v247, v239
	v_cvt_pk_bf16_f32 v232, v240, v241
	v_cvt_pk_bf16_f32 v233, v242, v243
	v_cvt_pk_bf16_f32 v234, v244, v245
	v_cvt_pk_bf16_f32 v235, v246, v247
	buffer_store_dwordx4 v[232:235], v251, s[72:75], 0 offen sc1
	s_setprio 2
	s_barrier
	v_mfma_f32_16x16x32_bf16 v[16:19], v[176:179], v[224:227], v[16:19]
	v_mfma_f32_16x16x32_bf16 v[8:11], v[184:187], v[224:227], v[8:11]
	s_setprio 0
	v_add_u32_e32 v155, s49, v148
	ds_read_b128 v[156:159], v155
	ds_read_b128 v[160:163], v155 offset:1024
	ds_read_b128 v[164:167], v155 offset:2048
	ds_read_b128 v[168:171], v155 offset:3072
	v_add_u32_e32 v155, s50, v148
	ds_read_b128 v[172:175], v155
	ds_read_b128 v[176:179], v155 offset:1024
	ds_read_b128 v[180:183], v155 offset:2048
	ds_read_b128 v[184:187], v155 offset:3072
	s_add_u32 s18, s64, 0x4000
	s_addc_u32 s19, s65, 0
	s_mov_b32 m0, s43
	ds_read_b128 v[192:195], v154 offset:32768
	ds_read_b128 v[200:203], v154 offset:33792
	ds_read_b128 v[204:207], v154 offset:34816
	ds_read_b128 v[208:211], v154 offset:35840
	ds_read_b128 v[212:215], v154 offset:36864
	ds_read_b128 v[216:219], v154 offset:37888
	ds_read_b128 v[220:223], v154 offset:38912
	ds_read_b128 v[224:227], v154 offset:39936
	global_load_lds_dwordx4 v130, s[18:19] sc1
	s_mov_b32 m0, s44
	s_nop 0
	global_load_lds_dwordx4 v128, s[18:19] sc1
	s_waitcnt vmcnt(16)
	s_waitcnt lgkmcnt(0)
	s_setprio 1
	s_barrier
	v_mfma_f32_16x16x32_bf16 v[116:119], v[156:159], v[192:195], v[116:119]
	v_mfma_f32_16x16x32_bf16 v[108:111], v[164:167], v[192:195], v[108:111]
	v_mfma_f32_16x16x32_bf16 v[100:103], v[156:159], v[204:207], v[100:103]
	v_mfma_f32_16x16x32_bf16 v[92:95], v[164:167], v[204:207], v[92:95]
	v_mfma_f32_16x16x32_bf16 v[84:87], v[156:159], v[212:215], v[84:87]
	v_mfma_f32_16x16x32_bf16 v[76:79], v[164:167], v[212:215], v[76:79]
	v_mfma_f32_16x16x32_bf16 v[60:63], v[156:159], v[220:223], v[60:63]
	v_mfma_f32_16x16x32_bf16 v[52:55], v[164:167], v[220:223], v[52:55]
	v_mfma_f32_16x16x32_bf16 v[116:119], v[160:163], v[200:203], v[116:119]
	v_mfma_f32_16x16x32_bf16 v[108:111], v[168:171], v[200:203], v[108:111]
	v_mfma_f32_16x16x32_bf16 v[100:103], v[160:163], v[208:211], v[100:103]
	v_mfma_f32_16x16x32_bf16 v[92:95], v[168:171], v[208:211], v[92:95]
	v_mfma_f32_16x16x32_bf16 v[84:87], v[160:163], v[216:219], v[84:87]
	v_mfma_f32_16x16x32_bf16 v[76:79], v[168:171], v[216:219], v[76:79]
	v_mfma_f32_16x16x32_bf16 v[60:63], v[160:163], v[224:227], v[60:63]
	v_mfma_f32_16x16x32_bf16 v[52:55], v[168:171], v[224:227], v[52:55]
	v_mfma_f32_16x16x32_bf16 v[124:127], v[172:175], v[192:195], v[124:127]
	v_mfma_f32_16x16x32_bf16 v[120:123], v[180:183], v[192:195], v[120:123]
	v_mfma_f32_16x16x32_bf16 v[112:115], v[172:175], v[204:207], v[112:115]
	v_mfma_f32_16x16x32_bf16 v[104:107], v[180:183], v[204:207], v[104:107]
	v_mfma_f32_16x16x32_bf16 v[96:99], v[172:175], v[212:215], v[96:99]
	v_mfma_f32_16x16x32_bf16 v[88:91], v[180:183], v[212:215], v[88:91]
	v_mfma_f32_16x16x32_bf16 v[80:83], v[172:175], v[220:223], v[80:83]
	v_mfma_f32_16x16x32_bf16 v[68:71], v[180:183], v[220:223], v[68:71]
	v_mfma_f32_16x16x32_bf16 v[124:127], v[176:179], v[200:203], v[124:127]
	v_mfma_f32_16x16x32_bf16 v[120:123], v[184:187], v[200:203], v[120:123]
	v_mfma_f32_16x16x32_bf16 v[112:115], v[176:179], v[208:211], v[112:115]
	v_mfma_f32_16x16x32_bf16 v[104:107], v[184:187], v[208:211], v[104:107]
	v_mfma_f32_16x16x32_bf16 v[96:99], v[176:179], v[216:219], v[96:99]
	v_mfma_f32_16x16x32_bf16 v[88:91], v[184:187], v[216:219], v[88:91]
	s_setprio 2
	s_barrier
	v_mfma_f32_16x16x32_bf16 v[80:83], v[176:179], v[224:227], v[80:83]
	v_mfma_f32_16x16x32_bf16 v[68:71], v[184:187], v[224:227], v[68:71]
	s_setprio 0
	s_add_u32 s18, s62, 0x8000
	s_addc_u32 s19, s63, 0
	s_add_i32 s64, s49, s36
	s_mov_b32 m0, s64
	ds_read_b128 v[192:195], v154 offset:49152
	ds_read_b128 v[200:203], v154 offset:50176
	ds_read_b128 v[204:207], v154 offset:51200
	ds_read_b128 v[208:211], v154 offset:52224
	ds_read_b128 v[212:215], v154 offset:53248
	ds_read_b128 v[216:219], v154 offset:54272
	ds_read_b128 v[220:223], v154 offset:55296
	ds_read_b128 v[224:227], v154 offset:56320
	global_load_lds_dwordx4 v132, s[18:19] sc1
	s_add_i32 m0, s64, 0x2000
	s_nop 0
	global_load_lds_dwordx4 v134, s[18:19] sc1
	s_add_u32 s18, s62, 0xc000
	s_addc_u32 s19, s63, 0
	s_add_i32 s62, s50, s36
	s_mov_b32 m0, s62
	s_nop 0
	global_load_lds_dwordx4 v132, s[18:19] sc1
	s_add_i32 m0, s62, 0x2000
	s_nop 0
	global_load_lds_dwordx4 v134, s[18:19] sc1
	s_mov_b32 m0, s7
	s_nop 0
	global_load_lds_dwordx4 v130, s[56:57] sc1
	s_mov_b32 m0, s45
	s_nop 0
	global_load_lds_dwordx4 v128, s[56:57] sc1
	s_waitcnt vmcnt(12)
	s_waitcnt lgkmcnt(0)
	s_setprio 1
	s_barrier
	v_mfma_f32_16x16x32_bf16 v[56:59], v[156:159], v[192:195], v[56:59]
	v_mfma_f32_16x16x32_bf16 v[44:47], v[164:167], v[192:195], v[44:47]
	v_mfma_f32_16x16x32_bf16 v[36:39], v[156:159], v[204:207], v[36:39]
	v_mfma_f32_16x16x32_bf16 v[28:31], v[164:167], v[204:207], v[28:31]
	v_mfma_f32_16x16x32_bf16 v[20:23], v[156:159], v[212:215], v[20:23]
	v_mfma_f32_16x16x32_bf16 v[12:15], v[164:167], v[212:215], v[12:15]
	v_mfma_f32_16x16x32_bf16 v[4:7], v[156:159], v[220:223], v[4:7]
	v_mfma_f32_16x16x32_bf16 v[0:3], v[164:167], v[220:223], v[0:3]
	v_mfma_f32_16x16x32_bf16 v[56:59], v[160:163], v[200:203], v[56:59]
	v_mfma_f32_16x16x32_bf16 v[44:47], v[168:171], v[200:203], v[44:47]
	v_mfma_f32_16x16x32_bf16 v[36:39], v[160:163], v[208:211], v[36:39]
	v_mfma_f32_16x16x32_bf16 v[28:31], v[168:171], v[208:211], v[28:31]
	v_mfma_f32_16x16x32_bf16 v[20:23], v[160:163], v[216:219], v[20:23]
	v_mfma_f32_16x16x32_bf16 v[12:15], v[168:171], v[216:219], v[12:15]
	v_mfma_f32_16x16x32_bf16 v[4:7], v[160:163], v[224:227], v[4:7]
	v_mfma_f32_16x16x32_bf16 v[0:3], v[168:171], v[224:227], v[0:3]
	v_mfma_f32_16x16x32_bf16 v[72:75], v[172:175], v[192:195], v[72:75]
	v_mfma_f32_16x16x32_bf16 v[64:67], v[180:183], v[192:195], v[64:67]
	v_mfma_f32_16x16x32_bf16 v[48:51], v[172:175], v[204:207], v[48:51]
	v_mfma_f32_16x16x32_bf16 v[40:43], v[180:183], v[204:207], v[40:43]
	v_mfma_f32_16x16x32_bf16 v[32:35], v[172:175], v[212:215], v[32:35]
	v_mfma_f32_16x16x32_bf16 v[24:27], v[180:183], v[212:215], v[24:27]
	v_mfma_f32_16x16x32_bf16 v[16:19], v[172:175], v[220:223], v[16:19]
	v_mfma_f32_16x16x32_bf16 v[8:11], v[180:183], v[220:223], v[8:11]
	v_mfma_f32_16x16x32_bf16 v[72:75], v[176:179], v[200:203], v[72:75]
	v_mfma_f32_16x16x32_bf16 v[64:67], v[184:187], v[200:203], v[64:67]
	v_mfma_f32_16x16x32_bf16 v[48:51], v[176:179], v[208:211], v[48:51]
	v_mfma_f32_16x16x32_bf16 v[40:43], v[184:187], v[208:211], v[40:43]
	v_mfma_f32_16x16x32_bf16 v[32:35], v[176:179], v[216:219], v[32:35]
	v_mfma_f32_16x16x32_bf16 v[24:27], v[184:187], v[216:219], v[24:27]
	s_setprio 2
	s_barrier
	v_mfma_f32_16x16x32_bf16 v[16:19], v[176:179], v[224:227], v[16:19]
	v_mfma_f32_16x16x32_bf16 v[8:11], v[184:187], v[224:227], v[8:11]
	s_setprio 0
	s_add_i32 s78, s78, 2
	s_add_u32 s76, s76, 0x10000
	s_addc_u32 s77, s77, 0
	s_cmp_gt_u32 s78, 13
	s_mov_b64 s[18:19], s[40:41]
	s_branch .LBB0_1093
